# unit boundary: trailing half takes its offset barrier right after its epilogue again (its reads / scheduler math / unit-start loads move behind it), no setprio
# speedup vs baseline: 1.0083x; 1.0083x over previous
.Lpeel_p1:
	s_waitcnt lgkmcnt(0)
	s_add_i32 s7, s4, 0xfff84000
	s_cmp_eq_u32 s6, 28
	s_cselect_b32 s17, s0, s7
	s_cselect_b32 s16, s1, s5
	s_or_b32 s7, s17, 0x4000
	s_mov_b32 m0, s79
	s_nop 0
	buffer_load_dwordx4 v242, s[24:27], s4 offen lds
	s_nop 0
	s_mov_b32 m0, s83
	s_nop 0
	buffer_load_dwordx4 v243, s[24:27], s4 offen lds
	s_waitcnt vmcnt(24)
	s_waitcnt lgkmcnt(0)
	s_barrier
	s_waitcnt lgkmcnt(7)
	v_mfma_f32_16x16x32_bf16 v[180:183], v[16:19], v[192:195], 0
	v_mfma_f32_16x16x32_bf16 v[164:167], v[24:27], v[192:195], 0
	s_waitcnt lgkmcnt(5)
	v_mfma_f32_16x16x32_bf16 v[148:151], v[16:19], v[200:203], 0
	v_mfma_f32_16x16x32_bf16 v[140:143], v[24:27], v[200:203], 0
	s_waitcnt lgkmcnt(3)
	v_mfma_f32_16x16x32_bf16 v[132:135], v[16:19], v[220:223], 0
	v_mfma_f32_16x16x32_bf16 v[124:127], v[24:27], v[220:223], 0
	s_waitcnt lgkmcnt(1)
	v_mfma_f32_16x16x32_bf16 v[116:119], v[16:19], v[228:231], 0
	v_mfma_f32_16x16x32_bf16 v[108:111], v[24:27], v[228:231], 0
	v_mfma_f32_16x16x32_bf16 v[180:183], v[20:23], v[196:199], v[180:183]
	v_mfma_f32_16x16x32_bf16 v[164:167], v[28:31], v[196:199], v[164:167]
	v_mfma_f32_16x16x32_bf16 v[148:151], v[20:23], v[204:207], v[148:151]
	v_mfma_f32_16x16x32_bf16 v[140:143], v[28:31], v[204:207], v[140:143]
	v_mfma_f32_16x16x32_bf16 v[132:135], v[20:23], v[224:227], v[132:135]
	v_mfma_f32_16x16x32_bf16 v[124:127], v[28:31], v[224:227], v[124:127]
	s_waitcnt lgkmcnt(0)
	v_mfma_f32_16x16x32_bf16 v[116:119], v[20:23], v[246:249], v[116:119]
	v_mfma_f32_16x16x32_bf16 v[108:111], v[28:31], v[246:249], v[108:111]
	v_mfma_f32_16x16x32_bf16 v[172:175], v[152:155], v[192:195], 0
	v_mfma_f32_16x16x32_bf16 v[156:159], v[168:171], v[192:195], 0
	v_mfma_f32_16x16x32_bf16 v[144:147], v[152:155], v[200:203], 0
	v_mfma_f32_16x16x32_bf16 v[136:139], v[168:171], v[200:203], 0
	v_mfma_f32_16x16x32_bf16 v[128:131], v[152:155], v[220:223], 0
	v_mfma_f32_16x16x32_bf16 v[120:123], v[168:171], v[220:223], 0
	v_mfma_f32_16x16x32_bf16 v[112:115], v[152:155], v[228:231], 0
	v_mfma_f32_16x16x32_bf16 v[104:107], v[168:171], v[228:231], 0
	v_mfma_f32_16x16x32_bf16 v[172:175], v[160:163], v[196:199], v[172:175]
	v_mfma_f32_16x16x32_bf16 v[156:159], v[176:179], v[196:199], v[156:159]
	v_mfma_f32_16x16x32_bf16 v[144:147], v[160:163], v[204:207], v[144:147]
	v_mfma_f32_16x16x32_bf16 v[136:139], v[176:179], v[204:207], v[136:139]
	v_mfma_f32_16x16x32_bf16 v[128:131], v[160:163], v[224:227], v[128:131]
	v_mfma_f32_16x16x32_bf16 v[120:123], v[176:179], v[224:227], v[120:123]
	v_mfma_f32_16x16x32_bf16 v[112:115], v[160:163], v[246:249], v[112:115]
	v_mfma_f32_16x16x32_bf16 v[104:107], v[176:179], v[246:249], v[104:107]
	s_barrier
	ds_read_b128 v[192:195], v245 offset:16384
	ds_read_b128 v[196:199], v245 offset:17408
	ds_read_b128 v[200:203], v245 offset:18432
	ds_read_b128 v[204:207], v245 offset:19456
	ds_read_b128 v[220:223], v245 offset:20480
	ds_read_b128 v[224:227], v245 offset:21504
	ds_read_b128 v[228:231], v245 offset:22528
	ds_read_b128 v[246:249], v245 offset:23552
	s_mov_b32 m0, s51
	s_nop 0
	buffer_load_dwordx4 v242, s[56:59], s16 offen lds
	s_add_i32 s18, s16, 0x80000
	s_mov_b32 m0, s52
	s_nop 0
	buffer_load_dwordx4 v243, s[56:59], s16 offen lds
	s_nop 0
	s_mov_b32 m0, s53
	s_nop 0
	buffer_load_dwordx4 v242, s[56:59], s18 offen lds
	s_nop 0
	s_mov_b32 m0, s55
	s_nop 0
	buffer_load_dwordx4 v243, s[56:59], s18 offen lds
	s_nop 0
	s_mov_b32 m0, s31
	s_nop 0
	buffer_load_dwordx4 v242, s[24:27], s17 offen lds
	s_nop 0
	s_mov_b32 m0, s68
	s_nop 0
	buffer_load_dwordx4 v243, s[24:27], s17 offen lds
	s_waitcnt vmcnt(24)
	s_waitcnt lgkmcnt(0)
	s_barrier
	s_waitcnt lgkmcnt(7)
	v_mfma_f32_16x16x32_bf16 v[76:79], v[16:19], v[192:195], 0
	v_mfma_f32_16x16x32_bf16 v[68:71], v[24:27], v[192:195], 0
	s_waitcnt lgkmcnt(5)
	v_mfma_f32_16x16x32_bf16 v[60:63], v[16:19], v[200:203], 0
	v_mfma_f32_16x16x32_bf16 v[52:55], v[24:27], v[200:203], 0
	s_waitcnt lgkmcnt(3)
	v_mfma_f32_16x16x32_bf16 v[44:47], v[16:19], v[220:223], 0
	v_mfma_f32_16x16x32_bf16 v[36:39], v[24:27], v[220:223], 0
	s_waitcnt lgkmcnt(1)
	v_mfma_f32_16x16x32_bf16 v[12:15], v[16:19], v[228:231], 0
	v_mfma_f32_16x16x32_bf16 v[4:7], v[24:27], v[228:231], 0
	v_mfma_f32_16x16x32_bf16 v[76:79], v[20:23], v[196:199], v[76:79]
	v_mfma_f32_16x16x32_bf16 v[68:71], v[28:31], v[196:199], v[68:71]
	v_mfma_f32_16x16x32_bf16 v[60:63], v[20:23], v[204:207], v[60:63]
	v_mfma_f32_16x16x32_bf16 v[52:55], v[28:31], v[204:207], v[52:55]
	v_mfma_f32_16x16x32_bf16 v[44:47], v[20:23], v[224:227], v[44:47]
	v_mfma_f32_16x16x32_bf16 v[36:39], v[28:31], v[224:227], v[36:39]
	s_waitcnt lgkmcnt(0)
	v_mfma_f32_16x16x32_bf16 v[12:15], v[20:23], v[246:249], v[12:15]
	v_mfma_f32_16x16x32_bf16 v[4:7], v[28:31], v[246:249], v[4:7]
	v_mfma_f32_16x16x32_bf16 v[40:43], v[152:155], v[220:223], 0
	v_mfma_f32_16x16x32_bf16 v[32:35], v[168:171], v[220:223], 0
	v_mfma_f32_16x16x32_bf16 v[8:11], v[152:155], v[228:231], 0
	v_mfma_f32_16x16x32_bf16 v[0:3], v[168:171], v[228:231], 0
	v_mfma_f32_16x16x32_bf16 v[16:19], v[152:155], v[192:195], 0
	v_mfma_f32_16x16x32_bf16 v[20:23], v[168:171], v[192:195], 0
	v_mfma_f32_16x16x32_bf16 v[24:27], v[152:155], v[200:203], 0
	v_mfma_f32_16x16x32_bf16 v[28:31], v[168:171], v[200:203], 0
	v_mfma_f32_16x16x32_bf16 v[40:43], v[160:163], v[224:227], v[40:43]
	v_mfma_f32_16x16x32_bf16 v[32:35], v[176:179], v[224:227], v[32:35]
	v_mfma_f32_16x16x32_bf16 v[8:11], v[160:163], v[246:249], v[8:11]
	v_mfma_f32_16x16x32_bf16 v[0:3], v[176:179], v[246:249], v[0:3]
	v_mfma_f32_16x16x32_bf16 v[16:19], v[160:163], v[196:199], v[16:19]
	v_mfma_f32_16x16x32_bf16 v[20:23], v[176:179], v[196:199], v[20:23]
	v_mfma_f32_16x16x32_bf16 v[24:27], v[160:163], v[204:207], v[24:27]
	v_mfma_f32_16x16x32_bf16 v[28:31], v[176:179], v[204:207], v[28:31]
	s_barrier
	v_add_u32_e32 v72, 0x18000, v83
	v_add_u32_e32 v80, 0x1c000, v83
	ds_read_b128 v[48:51], v72
	ds_read_b128 v[56:59], v72 offset:1024
	ds_read_b128 v[64:67], v72 offset:2048
	ds_read_b128 v[72:75], v72 offset:3072
	ds_read_b128 v[152:155], v80
	ds_read_b128 v[160:163], v80 offset:1024
	ds_read_b128 v[168:171], v80 offset:2048
	ds_read_b128 v[176:179], v80 offset:3072
	ds_read_b128 v[192:195], v245 offset:32768
	ds_read_b128 v[196:199], v245 offset:33792
	ds_read_b128 v[200:203], v245 offset:34816
	ds_read_b128 v[204:207], v245 offset:35840
	ds_read_b128 v[220:223], v245 offset:36864
	ds_read_b128 v[224:227], v245 offset:37888
	ds_read_b128 v[228:231], v245 offset:38912
	ds_read_b128 v[246:249], v245 offset:39936
	s_add_i32 s17, s17, 0x80000
	s_mov_b32 m0, s69
	s_nop 0
	buffer_load_dwordx4 v242, s[24:27], s17 offen lds
	s_nop 0
	s_mov_b32 m0, s70
	s_nop 0
	buffer_load_dwordx4 v243, s[24:27], s17 offen lds
	s_waitcnt vmcnt(8)
	s_waitcnt lgkmcnt(0)
	s_barrier
	s_waitcnt lgkmcnt(7)
	v_mfma_f32_16x16x32_bf16 v[180:183], v[48:51], v[192:195], v[180:183]
	v_mfma_f32_16x16x32_bf16 v[164:167], v[64:67], v[192:195], v[164:167]
	s_waitcnt lgkmcnt(5)
	v_mfma_f32_16x16x32_bf16 v[148:151], v[48:51], v[200:203], v[148:151]
	v_mfma_f32_16x16x32_bf16 v[140:143], v[64:67], v[200:203], v[140:143]
	s_waitcnt lgkmcnt(3)
	v_mfma_f32_16x16x32_bf16 v[132:135], v[48:51], v[220:223], v[132:135]
	v_mfma_f32_16x16x32_bf16 v[124:127], v[64:67], v[220:223], v[124:127]
	s_waitcnt lgkmcnt(1)
	v_mfma_f32_16x16x32_bf16 v[116:119], v[48:51], v[228:231], v[116:119]
	v_mfma_f32_16x16x32_bf16 v[108:111], v[64:67], v[228:231], v[108:111]
	v_mfma_f32_16x16x32_bf16 v[180:183], v[56:59], v[196:199], v[180:183]
	v_mfma_f32_16x16x32_bf16 v[164:167], v[72:75], v[196:199], v[164:167]
	v_mfma_f32_16x16x32_bf16 v[148:151], v[56:59], v[204:207], v[148:151]
	v_mfma_f32_16x16x32_bf16 v[140:143], v[72:75], v[204:207], v[140:143]
	v_mfma_f32_16x16x32_bf16 v[132:135], v[56:59], v[224:227], v[132:135]
	v_mfma_f32_16x16x32_bf16 v[124:127], v[72:75], v[224:227], v[124:127]
	s_waitcnt lgkmcnt(0)
	v_mfma_f32_16x16x32_bf16 v[116:119], v[56:59], v[246:249], v[116:119]
	v_mfma_f32_16x16x32_bf16 v[108:111], v[72:75], v[246:249], v[108:111]
	v_mfma_f32_16x16x32_bf16 v[172:175], v[152:155], v[192:195], v[172:175]
	v_mfma_f32_16x16x32_bf16 v[156:159], v[168:171], v[192:195], v[156:159]
	v_mfma_f32_16x16x32_bf16 v[144:147], v[152:155], v[200:203], v[144:147]
	v_mfma_f32_16x16x32_bf16 v[136:139], v[168:171], v[200:203], v[136:139]
	v_mfma_f32_16x16x32_bf16 v[128:131], v[152:155], v[220:223], v[128:131]
	v_mfma_f32_16x16x32_bf16 v[120:123], v[168:171], v[220:223], v[120:123]
	v_mfma_f32_16x16x32_bf16 v[112:115], v[152:155], v[228:231], v[112:115]
	v_mfma_f32_16x16x32_bf16 v[104:107], v[168:171], v[228:231], v[104:107]
	v_mfma_f32_16x16x32_bf16 v[172:175], v[160:163], v[196:199], v[172:175]
	v_mfma_f32_16x16x32_bf16 v[156:159], v[176:179], v[196:199], v[156:159]
	v_mfma_f32_16x16x32_bf16 v[144:147], v[160:163], v[204:207], v[144:147]
	v_mfma_f32_16x16x32_bf16 v[136:139], v[176:179], v[204:207], v[136:139]
	v_mfma_f32_16x16x32_bf16 v[128:131], v[160:163], v[224:227], v[128:131]
	v_mfma_f32_16x16x32_bf16 v[120:123], v[176:179], v[224:227], v[120:123]
	v_mfma_f32_16x16x32_bf16 v[112:115], v[160:163], v[246:249], v[112:115]
	v_mfma_f32_16x16x32_bf16 v[104:107], v[176:179], v[246:249], v[104:107]
	s_barrier
	ds_read_b128 v[192:195], v245 offset:49152
	ds_read_b128 v[196:199], v245 offset:50176
	ds_read_b128 v[200:203], v245 offset:51200
	ds_read_b128 v[204:207], v245 offset:52224
	ds_read_b128 v[220:223], v245 offset:53248
	ds_read_b128 v[224:227], v245 offset:54272
	ds_read_b128 v[228:231], v245 offset:55296
	ds_read_b128 v[246:249], v245 offset:56320
	s_or_b32 s17, s16, 0x4000
	s_mov_b32 m0, s73
	s_nop 0
	buffer_load_dwordx4 v242, s[56:59], s17 offen lds
	s_add_i32 s16, s16, 0x84000
	s_mov_b32 m0, s74
	s_nop 0
	buffer_load_dwordx4 v243, s[56:59], s17 offen lds
	s_nop 0
	s_mov_b32 m0, s77
	s_nop 0
	buffer_load_dwordx4 v242, s[56:59], s16 offen lds
	s_nop 0
	s_mov_b32 m0, s78
	s_nop 0
	buffer_load_dwordx4 v243, s[56:59], s16 offen lds
	s_nop 0
	s_mov_b32 m0, s75
	s_nop 0
	buffer_load_dwordx4 v242, s[24:27], s7 offen lds
	s_nop 0
	s_mov_b32 m0, s76
	s_nop 0
	buffer_load_dwordx4 v243, s[24:27], s7 offen lds
	s_waitcnt vmcnt(8)
	s_waitcnt lgkmcnt(0)
	s_barrier
	s_waitcnt lgkmcnt(7)
	v_mfma_f32_16x16x32_bf16 v[76:79], v[48:51], v[192:195], v[76:79]
	v_mfma_f32_16x16x32_bf16 v[68:71], v[64:67], v[192:195], v[68:71]
	s_waitcnt lgkmcnt(5)
	v_mfma_f32_16x16x32_bf16 v[60:63], v[48:51], v[200:203], v[60:63]
	v_mfma_f32_16x16x32_bf16 v[52:55], v[64:67], v[200:203], v[52:55]
	s_waitcnt lgkmcnt(3)
	v_mfma_f32_16x16x32_bf16 v[44:47], v[48:51], v[220:223], v[44:47]
	v_mfma_f32_16x16x32_bf16 v[36:39], v[64:67], v[220:223], v[36:39]
	s_waitcnt lgkmcnt(1)
	v_mfma_f32_16x16x32_bf16 v[12:15], v[48:51], v[228:231], v[12:15]
	v_mfma_f32_16x16x32_bf16 v[4:7], v[64:67], v[228:231], v[4:7]
	v_mfma_f32_16x16x32_bf16 v[76:79], v[56:59], v[196:199], v[76:79]
	v_mfma_f32_16x16x32_bf16 v[68:71], v[72:75], v[196:199], v[68:71]
	v_mfma_f32_16x16x32_bf16 v[60:63], v[56:59], v[204:207], v[60:63]
	v_mfma_f32_16x16x32_bf16 v[52:55], v[72:75], v[204:207], v[52:55]
	v_mfma_f32_16x16x32_bf16 v[44:47], v[56:59], v[224:227], v[44:47]
	v_mfma_f32_16x16x32_bf16 v[36:39], v[72:75], v[224:227], v[36:39]
	s_waitcnt lgkmcnt(0)
	v_mfma_f32_16x16x32_bf16 v[12:15], v[56:59], v[246:249], v[12:15]
	v_mfma_f32_16x16x32_bf16 v[4:7], v[72:75], v[246:249], v[4:7]
	v_mfma_f32_16x16x32_bf16 v[16:19], v[152:155], v[192:195], v[16:19]
	v_mfma_f32_16x16x32_bf16 v[72:75], v[160:163], v[196:199], v[16:19]
	v_mfma_f32_16x16x32_bf16 v[16:19], v[168:171], v[192:195], v[20:23]
	v_mfma_f32_16x16x32_bf16 v[64:67], v[176:179], v[196:199], v[16:19]
	v_mfma_f32_16x16x32_bf16 v[16:19], v[152:155], v[200:203], v[24:27]
	v_mfma_f32_16x16x32_bf16 v[56:59], v[160:163], v[204:207], v[16:19]
	v_mfma_f32_16x16x32_bf16 v[16:19], v[168:171], v[200:203], v[28:31]
	v_mfma_f32_16x16x32_bf16 v[48:51], v[176:179], v[204:207], v[16:19]
	v_mfma_f32_16x16x32_bf16 v[16:19], v[152:155], v[220:223], v[40:43]
	v_mfma_f32_16x16x32_bf16 v[40:43], v[160:163], v[224:227], v[16:19]
	v_mfma_f32_16x16x32_bf16 v[16:19], v[168:171], v[220:223], v[32:35]
	v_mfma_f32_16x16x32_bf16 v[8:11], v[152:155], v[228:231], v[8:11]
	v_mfma_f32_16x16x32_bf16 v[0:3], v[168:171], v[228:231], v[0:3]
	v_mfma_f32_16x16x32_bf16 v[32:35], v[176:179], v[224:227], v[16:19]
	v_mfma_f32_16x16x32_bf16 v[8:11], v[160:163], v[246:249], v[8:11]
	v_mfma_f32_16x16x32_bf16 v[0:3], v[176:179], v[246:249], v[0:3]
	s_barrier
	s_add_i32 s6, s6, 2
	s_add_i32 s4, s4, 0x8000
	s_add_i32 s5, s5, 0x8000

.Lpeel_p4:
	s_waitcnt lgkmcnt(0)
	s_add_i32 s11, s8, 0xfff84000
	s_cmp_eq_u32 s10, 28
	s_cselect_b32 s13, s6, s11
	s_cselect_b32 s12, s7, s9
	s_or_b32 s11, s13, 0x4000
	s_mov_b32 m0, s89
	s_nop 0
	buffer_load_dwordx4 v220, s[64:67], s8 offen lds
	s_nop 0
	s_mov_b32 m0, s91
	s_nop 0
	buffer_load_dwordx4 v221, s[64:67], s8 offen lds
	s_waitcnt vmcnt(24)
	s_waitcnt lgkmcnt(0)
	s_barrier
	s_waitcnt lgkmcnt(7)
	v_mfma_f32_16x16x32_bf16 v[164:167], v[128:131], v[184:187], 0
	v_mfma_f32_16x16x32_bf16 v[160:163], v[152:155], v[184:187], 0
	s_waitcnt lgkmcnt(5)
	v_mfma_f32_16x16x32_bf16 v[136:139], v[128:131], v[192:195], 0
	v_mfma_f32_16x16x32_bf16 v[132:135], v[152:155], v[192:195], 0
	s_waitcnt lgkmcnt(3)
	v_mfma_f32_16x16x32_bf16 v[116:119], v[128:131], v[200:203], 0
	v_mfma_f32_16x16x32_bf16 v[112:115], v[152:155], v[200:203], 0
	s_waitcnt lgkmcnt(1)
	v_mfma_f32_16x16x32_bf16 v[76:79], v[128:131], v[224:227], 0
	v_mfma_f32_16x16x32_bf16 v[72:75], v[152:155], v[224:227], 0
	v_mfma_f32_16x16x32_bf16 v[164:167], v[140:143], v[188:191], v[164:167]
	v_mfma_f32_16x16x32_bf16 v[160:163], v[156:159], v[188:191], v[160:163]
	v_mfma_f32_16x16x32_bf16 v[136:139], v[140:143], v[196:199], v[136:139]
	v_mfma_f32_16x16x32_bf16 v[132:135], v[156:159], v[196:199], v[132:135]
	v_mfma_f32_16x16x32_bf16 v[116:119], v[140:143], v[204:207], v[116:119]
	v_mfma_f32_16x16x32_bf16 v[112:115], v[156:159], v[204:207], v[112:115]
	s_waitcnt lgkmcnt(0)
	v_mfma_f32_16x16x32_bf16 v[76:79], v[140:143], v[228:231], v[76:79]
	v_mfma_f32_16x16x32_bf16 v[72:75], v[156:159], v[228:231], v[72:75]
	v_mfma_f32_16x16x32_bf16 v[148:151], v[168:171], v[184:187], 0
	v_mfma_f32_16x16x32_bf16 v[144:147], v[176:179], v[184:187], 0
	v_mfma_f32_16x16x32_bf16 v[124:127], v[168:171], v[192:195], 0
	v_mfma_f32_16x16x32_bf16 v[120:123], v[176:179], v[192:195], 0
	v_mfma_f32_16x16x32_bf16 v[108:111], v[168:171], v[200:203], 0
	v_mfma_f32_16x16x32_bf16 v[104:107], v[176:179], v[200:203], 0
	v_mfma_f32_16x16x32_bf16 v[68:71], v[168:171], v[224:227], 0
	v_mfma_f32_16x16x32_bf16 v[64:67], v[176:179], v[224:227], 0
	v_mfma_f32_16x16x32_bf16 v[148:151], v[172:175], v[188:191], v[148:151]
	v_mfma_f32_16x16x32_bf16 v[144:147], v[180:183], v[188:191], v[144:147]
	v_mfma_f32_16x16x32_bf16 v[124:127], v[172:175], v[196:199], v[124:127]
	v_mfma_f32_16x16x32_bf16 v[120:123], v[180:183], v[196:199], v[120:123]
	v_mfma_f32_16x16x32_bf16 v[108:111], v[172:175], v[204:207], v[108:111]
	v_mfma_f32_16x16x32_bf16 v[104:107], v[180:183], v[204:207], v[104:107]
	v_mfma_f32_16x16x32_bf16 v[68:71], v[172:175], v[228:231], v[68:71]
	v_mfma_f32_16x16x32_bf16 v[64:67], v[180:183], v[228:231], v[64:67]
	s_barrier
	ds_read_b128 v[184:187], v223 offset:16384
	ds_read_b128 v[188:191], v223 offset:17408
	ds_read_b128 v[192:195], v223 offset:18432
	ds_read_b128 v[196:199], v223 offset:19456
	ds_read_b128 v[200:203], v223 offset:20480
	ds_read_b128 v[204:207], v223 offset:21504
	ds_read_b128 v[224:227], v223 offset:22528
	ds_read_b128 v[228:231], v223 offset:23552
	s_mov_b32 m0, s55
	s_nop 0
	buffer_load_dwordx4 v220, s[48:51], s12 offen lds
	s_add_i32 s14, s12, 0x80000
	s_mov_b32 m0, s76
	s_nop 0
	buffer_load_dwordx4 v221, s[48:51], s12 offen lds
	s_nop 0
	s_mov_b32 m0, s77
	s_nop 0
	buffer_load_dwordx4 v220, s[48:51], s14 offen lds
	s_nop 0
	s_mov_b32 m0, s78
	s_nop 0
	buffer_load_dwordx4 v221, s[48:51], s14 offen lds
	s_nop 0
	s_mov_b32 m0, s31
	s_nop 0
	buffer_load_dwordx4 v220, s[64:67], s13 offen lds
	s_nop 0
	s_mov_b32 m0, s79
	s_nop 0
	buffer_load_dwordx4 v221, s[64:67], s13 offen lds
	s_waitcnt vmcnt(24)
	s_waitcnt lgkmcnt(0)
	s_barrier
	s_waitcnt lgkmcnt(7)
	v_mfma_f32_16x16x32_bf16 v[60:63], v[128:131], v[184:187], 0
	v_mfma_f32_16x16x32_bf16 v[56:59], v[152:155], v[184:187], 0
	s_waitcnt lgkmcnt(5)
	v_mfma_f32_16x16x32_bf16 v[44:47], v[128:131], v[192:195], 0
	v_mfma_f32_16x16x32_bf16 v[40:43], v[152:155], v[192:195], 0
	s_waitcnt lgkmcnt(3)
	v_mfma_f32_16x16x32_bf16 v[28:31], v[128:131], v[200:203], 0
	v_mfma_f32_16x16x32_bf16 v[24:27], v[152:155], v[200:203], 0
	s_waitcnt lgkmcnt(1)
	v_mfma_f32_16x16x32_bf16 v[12:15], v[128:131], v[224:227], 0
	v_mfma_f32_16x16x32_bf16 v[8:11], v[152:155], v[224:227], 0
	v_mfma_f32_16x16x32_bf16 v[60:63], v[140:143], v[188:191], v[60:63]
	v_mfma_f32_16x16x32_bf16 v[56:59], v[156:159], v[188:191], v[56:59]
	v_mfma_f32_16x16x32_bf16 v[44:47], v[140:143], v[196:199], v[44:47]
	v_mfma_f32_16x16x32_bf16 v[40:43], v[156:159], v[196:199], v[40:43]
	v_mfma_f32_16x16x32_bf16 v[28:31], v[140:143], v[204:207], v[28:31]
	v_mfma_f32_16x16x32_bf16 v[24:27], v[156:159], v[204:207], v[24:27]
	s_waitcnt lgkmcnt(0)
	v_mfma_f32_16x16x32_bf16 v[12:15], v[140:143], v[228:231], v[12:15]
	v_mfma_f32_16x16x32_bf16 v[8:11], v[156:159], v[228:231], v[8:11]
	v_mfma_f32_16x16x32_bf16 v[52:55], v[168:171], v[184:187], 0
	v_mfma_f32_16x16x32_bf16 v[48:51], v[176:179], v[184:187], 0
	v_mfma_f32_16x16x32_bf16 v[36:39], v[168:171], v[192:195], 0
	v_mfma_f32_16x16x32_bf16 v[32:35], v[176:179], v[192:195], 0
	v_mfma_f32_16x16x32_bf16 v[20:23], v[168:171], v[200:203], 0
	v_mfma_f32_16x16x32_bf16 v[16:19], v[176:179], v[200:203], 0
	v_mfma_f32_16x16x32_bf16 v[4:7], v[168:171], v[224:227], 0
	v_mfma_f32_16x16x32_bf16 v[0:3], v[176:179], v[224:227], 0
	v_mfma_f32_16x16x32_bf16 v[52:55], v[172:175], v[188:191], v[52:55]
	v_mfma_f32_16x16x32_bf16 v[48:51], v[180:183], v[188:191], v[48:51]
	v_mfma_f32_16x16x32_bf16 v[36:39], v[172:175], v[196:199], v[36:39]
	v_mfma_f32_16x16x32_bf16 v[32:35], v[180:183], v[196:199], v[32:35]
	v_mfma_f32_16x16x32_bf16 v[20:23], v[172:175], v[204:207], v[20:23]
	v_mfma_f32_16x16x32_bf16 v[16:19], v[180:183], v[204:207], v[16:19]
	v_mfma_f32_16x16x32_bf16 v[4:7], v[172:175], v[228:231], v[4:7]
	v_mfma_f32_16x16x32_bf16 v[0:3], v[180:183], v[228:231], v[0:3]
	s_barrier
	v_add_u32_e32 v156, 0x18000, v222
	v_add_u32_e32 v180, 0x1c000, v222
	ds_read_b128 v[128:131], v156
	ds_read_b128 v[140:143], v156 offset:1024
	ds_read_b128 v[152:155], v156 offset:2048
	ds_read_b128 v[156:159], v156 offset:3072
	ds_read_b128 v[168:171], v180
	ds_read_b128 v[172:175], v180 offset:1024
	ds_read_b128 v[176:179], v180 offset:2048
	ds_read_b128 v[180:183], v180 offset:3072
	ds_read_b128 v[184:187], v223 offset:32768
	ds_read_b128 v[188:191], v223 offset:33792
	ds_read_b128 v[192:195], v223 offset:34816
	ds_read_b128 v[196:199], v223 offset:35840
	ds_read_b128 v[200:203], v223 offset:36864
	ds_read_b128 v[204:207], v223 offset:37888
	ds_read_b128 v[224:227], v223 offset:38912
	ds_read_b128 v[228:231], v223 offset:39936
	s_add_i32 s13, s13, 0x80000
	s_mov_b32 m0, s82
	s_nop 0
	buffer_load_dwordx4 v220, s[64:67], s13 offen lds
	s_nop 0
	s_mov_b32 m0, s83
	s_nop 0
	buffer_load_dwordx4 v221, s[64:67], s13 offen lds
	s_waitcnt vmcnt(8)
	s_waitcnt lgkmcnt(0)
	s_barrier
	s_waitcnt lgkmcnt(7)
	v_mfma_f32_16x16x32_bf16 v[164:167], v[128:131], v[184:187], v[164:167]
	v_mfma_f32_16x16x32_bf16 v[160:163], v[152:155], v[184:187], v[160:163]
	s_waitcnt lgkmcnt(5)
	v_mfma_f32_16x16x32_bf16 v[136:139], v[128:131], v[192:195], v[136:139]
	v_mfma_f32_16x16x32_bf16 v[132:135], v[152:155], v[192:195], v[132:135]
	s_waitcnt lgkmcnt(3)
	v_mfma_f32_16x16x32_bf16 v[116:119], v[128:131], v[200:203], v[116:119]
	v_mfma_f32_16x16x32_bf16 v[112:115], v[152:155], v[200:203], v[112:115]
	s_waitcnt lgkmcnt(1)
	v_mfma_f32_16x16x32_bf16 v[76:79], v[128:131], v[224:227], v[76:79]
	v_mfma_f32_16x16x32_bf16 v[72:75], v[152:155], v[224:227], v[72:75]
	v_mfma_f32_16x16x32_bf16 v[164:167], v[140:143], v[188:191], v[164:167]
	v_mfma_f32_16x16x32_bf16 v[160:163], v[156:159], v[188:191], v[160:163]
	v_mfma_f32_16x16x32_bf16 v[136:139], v[140:143], v[196:199], v[136:139]
	v_mfma_f32_16x16x32_bf16 v[132:135], v[156:159], v[196:199], v[132:135]
	v_mfma_f32_16x16x32_bf16 v[116:119], v[140:143], v[204:207], v[116:119]
	v_mfma_f32_16x16x32_bf16 v[112:115], v[156:159], v[204:207], v[112:115]
	s_waitcnt lgkmcnt(0)
	v_mfma_f32_16x16x32_bf16 v[76:79], v[140:143], v[228:231], v[76:79]
	v_mfma_f32_16x16x32_bf16 v[72:75], v[156:159], v[228:231], v[72:75]
	v_mfma_f32_16x16x32_bf16 v[148:151], v[168:171], v[184:187], v[148:151]
	v_mfma_f32_16x16x32_bf16 v[144:147], v[176:179], v[184:187], v[144:147]
	v_mfma_f32_16x16x32_bf16 v[124:127], v[168:171], v[192:195], v[124:127]
	v_mfma_f32_16x16x32_bf16 v[120:123], v[176:179], v[192:195], v[120:123]
	v_mfma_f32_16x16x32_bf16 v[108:111], v[168:171], v[200:203], v[108:111]
	v_mfma_f32_16x16x32_bf16 v[104:107], v[176:179], v[200:203], v[104:107]
	v_mfma_f32_16x16x32_bf16 v[68:71], v[168:171], v[224:227], v[68:71]
	v_mfma_f32_16x16x32_bf16 v[64:67], v[176:179], v[224:227], v[64:67]
	v_mfma_f32_16x16x32_bf16 v[148:151], v[172:175], v[188:191], v[148:151]
	v_mfma_f32_16x16x32_bf16 v[144:147], v[180:183], v[188:191], v[144:147]
	v_mfma_f32_16x16x32_bf16 v[124:127], v[172:175], v[196:199], v[124:127]
	v_mfma_f32_16x16x32_bf16 v[120:123], v[180:183], v[196:199], v[120:123]
	v_mfma_f32_16x16x32_bf16 v[108:111], v[172:175], v[204:207], v[108:111]
	v_mfma_f32_16x16x32_bf16 v[104:107], v[180:183], v[204:207], v[104:107]
	v_mfma_f32_16x16x32_bf16 v[68:71], v[172:175], v[228:231], v[68:71]
	v_mfma_f32_16x16x32_bf16 v[64:67], v[180:183], v[228:231], v[64:67]
	s_barrier
	ds_read_b128 v[184:187], v223 offset:49152
	ds_read_b128 v[188:191], v223 offset:50176
	ds_read_b128 v[192:195], v223 offset:51200
	ds_read_b128 v[196:199], v223 offset:52224
	ds_read_b128 v[200:203], v223 offset:53248
	ds_read_b128 v[204:207], v223 offset:54272
	ds_read_b128 v[224:227], v223 offset:55296
	ds_read_b128 v[228:231], v223 offset:56320
	s_or_b32 s13, s12, 0x4000
	s_mov_b32 m0, s34
	s_nop 0
	buffer_load_dwordx4 v220, s[48:51], s13 offen lds
	s_add_i32 s12, s12, 0x84000
	s_mov_b32 m0, s84
	s_nop 0
	buffer_load_dwordx4 v221, s[48:51], s13 offen lds
	s_nop 0
	s_mov_b32 m0, s87
	s_nop 0
	buffer_load_dwordx4 v220, s[48:51], s12 offen lds
	s_nop 0
	s_mov_b32 m0, s88
	s_nop 0
	buffer_load_dwordx4 v221, s[48:51], s12 offen lds
	s_nop 0
	s_mov_b32 m0, s85
	s_nop 0
	buffer_load_dwordx4 v220, s[64:67], s11 offen lds
	s_nop 0
	s_mov_b32 m0, s86
	s_nop 0
	buffer_load_dwordx4 v221, s[64:67], s11 offen lds
	s_waitcnt vmcnt(8)
	s_waitcnt lgkmcnt(0)
	s_barrier
	s_waitcnt lgkmcnt(7)
	v_mfma_f32_16x16x32_bf16 v[60:63], v[128:131], v[184:187], v[60:63]
	v_mfma_f32_16x16x32_bf16 v[56:59], v[152:155], v[184:187], v[56:59]
	s_waitcnt lgkmcnt(5)
	v_mfma_f32_16x16x32_bf16 v[44:47], v[128:131], v[192:195], v[44:47]
	v_mfma_f32_16x16x32_bf16 v[40:43], v[152:155], v[192:195], v[40:43]
	s_waitcnt lgkmcnt(3)
	v_mfma_f32_16x16x32_bf16 v[28:31], v[128:131], v[200:203], v[28:31]
	v_mfma_f32_16x16x32_bf16 v[24:27], v[152:155], v[200:203], v[24:27]
	s_waitcnt lgkmcnt(1)
	v_mfma_f32_16x16x32_bf16 v[12:15], v[128:131], v[224:227], v[12:15]
	v_mfma_f32_16x16x32_bf16 v[8:11], v[152:155], v[224:227], v[8:11]
	v_mfma_f32_16x16x32_bf16 v[60:63], v[140:143], v[188:191], v[60:63]
	v_mfma_f32_16x16x32_bf16 v[56:59], v[156:159], v[188:191], v[56:59]
	v_mfma_f32_16x16x32_bf16 v[44:47], v[140:143], v[196:199], v[44:47]
	v_mfma_f32_16x16x32_bf16 v[40:43], v[156:159], v[196:199], v[40:43]
	v_mfma_f32_16x16x32_bf16 v[28:31], v[140:143], v[204:207], v[28:31]
	v_mfma_f32_16x16x32_bf16 v[24:27], v[156:159], v[204:207], v[24:27]
	s_waitcnt lgkmcnt(0)
	v_mfma_f32_16x16x32_bf16 v[12:15], v[140:143], v[228:231], v[12:15]
	v_mfma_f32_16x16x32_bf16 v[8:11], v[156:159], v[228:231], v[8:11]
	v_mfma_f32_16x16x32_bf16 v[52:55], v[168:171], v[184:187], v[52:55]
	v_mfma_f32_16x16x32_bf16 v[48:51], v[176:179], v[184:187], v[48:51]
	v_mfma_f32_16x16x32_bf16 v[36:39], v[168:171], v[192:195], v[36:39]
	v_mfma_f32_16x16x32_bf16 v[32:35], v[176:179], v[192:195], v[32:35]
	v_mfma_f32_16x16x32_bf16 v[20:23], v[168:171], v[200:203], v[20:23]
	v_mfma_f32_16x16x32_bf16 v[16:19], v[176:179], v[200:203], v[16:19]
	v_mfma_f32_16x16x32_bf16 v[4:7], v[168:171], v[224:227], v[4:7]
	v_mfma_f32_16x16x32_bf16 v[0:3], v[176:179], v[224:227], v[0:3]
	v_mfma_f32_16x16x32_bf16 v[52:55], v[172:175], v[188:191], v[52:55]
	v_mfma_f32_16x16x32_bf16 v[48:51], v[180:183], v[188:191], v[48:51]
	v_mfma_f32_16x16x32_bf16 v[36:39], v[172:175], v[196:199], v[36:39]
	v_mfma_f32_16x16x32_bf16 v[32:35], v[180:183], v[196:199], v[32:35]
	v_mfma_f32_16x16x32_bf16 v[20:23], v[172:175], v[204:207], v[20:23]
	v_mfma_f32_16x16x32_bf16 v[16:19], v[180:183], v[204:207], v[16:19]
	v_mfma_f32_16x16x32_bf16 v[4:7], v[172:175], v[228:231], v[4:7]
	v_mfma_f32_16x16x32_bf16 v[0:3], v[180:183], v[228:231], v[0:3]
	s_barrier
	s_add_i32 s10, s10, 2
	s_add_i32 s8, s8, 0x8000
	s_add_i32 s9, s9, 0x8000

.Lpeel_p5:
	s_waitcnt lgkmcnt(0)
	s_add_i32 s53, s37, 0xfff84000
	s_cmp_eq_u32 s52, 28
	s_cselect_b32 s56, s4, s53
	s_cselect_b32 s55, s5, s51
	s_or_b32 s53, s56, 0x4000
	s_mov_b32 m0, s41
	s_nop 0
	buffer_load_dwordx4 v166, s[24:27], s37 offen lds
	s_nop 0
	s_mov_b32 m0, s42
	s_nop 0
	buffer_load_dwordx4 v167, s[24:27], s37 offen lds
	s_waitcnt vmcnt(24)
	s_waitcnt lgkmcnt(0)
	s_barrier
	s_waitcnt lgkmcnt(7)
	v_mfma_f32_16x16x32_bf16 v[148:151], v[152:155], v[190:193], 0
	v_mfma_f32_16x16x32_bf16 v[140:143], v[160:163], v[190:193], 0
	s_waitcnt lgkmcnt(5)
	v_mfma_f32_16x16x32_bf16 v[132:135], v[152:155], v[198:201], 0
	v_mfma_f32_16x16x32_bf16 v[124:127], v[160:163], v[198:201], 0
	s_waitcnt lgkmcnt(3)
	v_mfma_f32_16x16x32_bf16 v[116:119], v[152:155], v[220:223], 0
	v_mfma_f32_16x16x32_bf16 v[108:111], v[160:163], v[220:223], 0
	s_waitcnt lgkmcnt(1)
	v_mfma_f32_16x16x32_bf16 v[76:79], v[152:155], v[228:231], 0
	v_mfma_f32_16x16x32_bf16 v[68:71], v[160:163], v[228:231], 0
	v_mfma_f32_16x16x32_bf16 v[148:151], v[156:159], v[194:197], v[148:151]
	v_mfma_f32_16x16x32_bf16 v[140:143], v[170:173], v[194:197], v[140:143]
	v_mfma_f32_16x16x32_bf16 v[132:135], v[156:159], v[202:205], v[132:135]
	v_mfma_f32_16x16x32_bf16 v[124:127], v[170:173], v[202:205], v[124:127]
	v_mfma_f32_16x16x32_bf16 v[116:119], v[156:159], v[224:227], v[116:119]
	v_mfma_f32_16x16x32_bf16 v[108:111], v[170:173], v[224:227], v[108:111]
	s_waitcnt lgkmcnt(0)
	v_mfma_f32_16x16x32_bf16 v[76:79], v[156:159], v[240:243], v[76:79]
	v_mfma_f32_16x16x32_bf16 v[68:71], v[170:173], v[240:243], v[68:71]
	v_mfma_f32_16x16x32_bf16 v[144:147], v[174:177], v[190:193], 0
	v_mfma_f32_16x16x32_bf16 v[136:139], v[182:185], v[190:193], 0
	v_mfma_f32_16x16x32_bf16 v[128:131], v[174:177], v[198:201], 0
	v_mfma_f32_16x16x32_bf16 v[120:123], v[182:185], v[198:201], 0
	v_mfma_f32_16x16x32_bf16 v[112:115], v[174:177], v[220:223], 0
	v_mfma_f32_16x16x32_bf16 v[104:107], v[182:185], v[220:223], 0
	v_mfma_f32_16x16x32_bf16 v[72:75], v[174:177], v[228:231], 0
	v_mfma_f32_16x16x32_bf16 v[64:67], v[182:185], v[228:231], 0
	v_mfma_f32_16x16x32_bf16 v[144:147], v[178:181], v[194:197], v[144:147]
	v_mfma_f32_16x16x32_bf16 v[136:139], v[186:189], v[194:197], v[136:139]
	v_mfma_f32_16x16x32_bf16 v[128:131], v[178:181], v[202:205], v[128:131]
	v_mfma_f32_16x16x32_bf16 v[120:123], v[186:189], v[202:205], v[120:123]
	v_mfma_f32_16x16x32_bf16 v[112:115], v[178:181], v[224:227], v[112:115]
	v_mfma_f32_16x16x32_bf16 v[104:107], v[186:189], v[224:227], v[104:107]
	v_mfma_f32_16x16x32_bf16 v[72:75], v[178:181], v[240:243], v[72:75]
	v_mfma_f32_16x16x32_bf16 v[64:67], v[186:189], v[240:243], v[64:67]
	s_barrier
	ds_read_b128 v[190:193], v169 offset:16384
	ds_read_b128 v[194:197], v169 offset:17408
	ds_read_b128 v[198:201], v169 offset:18432
	ds_read_b128 v[202:205], v169 offset:19456
	ds_read_b128 v[220:223], v169 offset:20480
	ds_read_b128 v[224:227], v169 offset:21504
	ds_read_b128 v[228:231], v169 offset:22528
	ds_read_b128 v[240:243], v169 offset:23552
	s_mov_b32 m0, s7
	s_nop 0
	buffer_load_dwordx4 v166, s[28:31], s55 offen lds
	s_add_i32 s57, s55, 0x80000
	s_mov_b32 m0, s8
	s_nop 0
	buffer_load_dwordx4 v167, s[28:31], s55 offen lds
	s_nop 0
	s_mov_b32 m0, s9
	s_nop 0
	buffer_load_dwordx4 v166, s[28:31], s57 offen lds
	s_nop 0
	s_mov_b32 m0, s10
	s_nop 0
	buffer_load_dwordx4 v167, s[28:31], s57 offen lds
	s_nop 0
	s_mov_b32 m0, s6
	s_nop 0
	buffer_load_dwordx4 v166, s[24:27], s56 offen lds
	s_nop 0
	s_mov_b32 m0, s11
	s_nop 0
	buffer_load_dwordx4 v167, s[24:27], s56 offen lds
	s_waitcnt vmcnt(24)
	s_waitcnt lgkmcnt(0)
	s_barrier
	s_waitcnt lgkmcnt(7)
	v_mfma_f32_16x16x32_bf16 v[60:63], v[152:155], v[190:193], 0
	v_mfma_f32_16x16x32_bf16 v[52:55], v[160:163], v[190:193], 0
	s_waitcnt lgkmcnt(5)
	v_mfma_f32_16x16x32_bf16 v[44:47], v[152:155], v[198:201], 0
	v_mfma_f32_16x16x32_bf16 v[36:39], v[160:163], v[198:201], 0
	s_waitcnt lgkmcnt(3)
	v_mfma_f32_16x16x32_bf16 v[28:31], v[152:155], v[220:223], 0
	v_mfma_f32_16x16x32_bf16 v[20:23], v[160:163], v[220:223], 0
	s_waitcnt lgkmcnt(1)
	v_mfma_f32_16x16x32_bf16 v[12:15], v[152:155], v[228:231], 0
	v_mfma_f32_16x16x32_bf16 v[4:7], v[160:163], v[228:231], 0
	v_mfma_f32_16x16x32_bf16 v[60:63], v[156:159], v[194:197], v[60:63]
	v_mfma_f32_16x16x32_bf16 v[52:55], v[170:173], v[194:197], v[52:55]
	v_mfma_f32_16x16x32_bf16 v[44:47], v[156:159], v[202:205], v[44:47]
	v_mfma_f32_16x16x32_bf16 v[36:39], v[170:173], v[202:205], v[36:39]
	v_mfma_f32_16x16x32_bf16 v[28:31], v[156:159], v[224:227], v[28:31]
	v_mfma_f32_16x16x32_bf16 v[20:23], v[170:173], v[224:227], v[20:23]
	s_waitcnt lgkmcnt(0)
	v_mfma_f32_16x16x32_bf16 v[12:15], v[156:159], v[240:243], v[12:15]
	v_mfma_f32_16x16x32_bf16 v[4:7], v[170:173], v[240:243], v[4:7]
	v_mfma_f32_16x16x32_bf16 v[56:59], v[174:177], v[190:193], 0
	v_mfma_f32_16x16x32_bf16 v[48:51], v[182:185], v[190:193], 0
	v_mfma_f32_16x16x32_bf16 v[40:43], v[174:177], v[198:201], 0
	v_mfma_f32_16x16x32_bf16 v[32:35], v[182:185], v[198:201], 0
	v_mfma_f32_16x16x32_bf16 v[24:27], v[174:177], v[220:223], 0
	v_mfma_f32_16x16x32_bf16 v[16:19], v[182:185], v[220:223], 0
	v_mfma_f32_16x16x32_bf16 v[8:11], v[174:177], v[228:231], 0
	v_mfma_f32_16x16x32_bf16 v[0:3], v[182:185], v[228:231], 0
	v_mfma_f32_16x16x32_bf16 v[56:59], v[178:181], v[194:197], v[56:59]
	v_mfma_f32_16x16x32_bf16 v[48:51], v[186:189], v[194:197], v[48:51]
	v_mfma_f32_16x16x32_bf16 v[40:43], v[178:181], v[202:205], v[40:43]
	v_mfma_f32_16x16x32_bf16 v[32:35], v[186:189], v[202:205], v[32:35]
	v_mfma_f32_16x16x32_bf16 v[24:27], v[178:181], v[224:227], v[24:27]
	v_mfma_f32_16x16x32_bf16 v[16:19], v[186:189], v[224:227], v[16:19]
	v_mfma_f32_16x16x32_bf16 v[8:11], v[178:181], v[240:243], v[8:11]
	v_mfma_f32_16x16x32_bf16 v[0:3], v[186:189], v[240:243], v[0:3]
	s_barrier
	v_add_u32_e32 v164, 0x18000, v168
	ds_read_b128 v[152:155], v164
	ds_read_b128 v[156:159], v164 offset:1024
	ds_read_b128 v[160:163], v164 offset:2048
	ds_read_b128 v[170:173], v164 offset:3072
	v_add_u32_e32 v164, 0x1c000, v168
	ds_read_b128 v[174:177], v164
	ds_read_b128 v[178:181], v164 offset:1024
	ds_read_b128 v[182:185], v164 offset:2048
	ds_read_b128 v[186:189], v164 offset:3072
	ds_read_b128 v[190:193], v169 offset:32768
	ds_read_b128 v[194:197], v169 offset:33792
	ds_read_b128 v[198:201], v169 offset:34816
	ds_read_b128 v[202:205], v169 offset:35840
	ds_read_b128 v[220:223], v169 offset:36864
	ds_read_b128 v[224:227], v169 offset:37888
	ds_read_b128 v[228:231], v169 offset:38912
	ds_read_b128 v[240:243], v169 offset:39936
	s_add_i32 s56, s56, 0x80000
	s_mov_b32 m0, s12
	s_nop 0
	buffer_load_dwordx4 v166, s[24:27], s56 offen lds
	s_nop 0
	s_mov_b32 m0, s13
	s_nop 0
	buffer_load_dwordx4 v167, s[24:27], s56 offen lds
	s_waitcnt vmcnt(8)
	s_waitcnt lgkmcnt(0)
	s_barrier
	s_waitcnt lgkmcnt(7)
	v_mfma_f32_16x16x32_bf16 v[148:151], v[152:155], v[190:193], v[148:151]
	v_mfma_f32_16x16x32_bf16 v[140:143], v[160:163], v[190:193], v[140:143]
	s_waitcnt lgkmcnt(5)
	v_mfma_f32_16x16x32_bf16 v[132:135], v[152:155], v[198:201], v[132:135]
	v_mfma_f32_16x16x32_bf16 v[124:127], v[160:163], v[198:201], v[124:127]
	s_waitcnt lgkmcnt(3)
	v_mfma_f32_16x16x32_bf16 v[116:119], v[152:155], v[220:223], v[116:119]
	v_mfma_f32_16x16x32_bf16 v[108:111], v[160:163], v[220:223], v[108:111]
	s_waitcnt lgkmcnt(1)
	v_mfma_f32_16x16x32_bf16 v[76:79], v[152:155], v[228:231], v[76:79]
	v_mfma_f32_16x16x32_bf16 v[68:71], v[160:163], v[228:231], v[68:71]
	v_mfma_f32_16x16x32_bf16 v[148:151], v[156:159], v[194:197], v[148:151]
	v_mfma_f32_16x16x32_bf16 v[140:143], v[170:173], v[194:197], v[140:143]
	v_mfma_f32_16x16x32_bf16 v[132:135], v[156:159], v[202:205], v[132:135]
	v_mfma_f32_16x16x32_bf16 v[124:127], v[170:173], v[202:205], v[124:127]
	v_mfma_f32_16x16x32_bf16 v[116:119], v[156:159], v[224:227], v[116:119]
	v_mfma_f32_16x16x32_bf16 v[108:111], v[170:173], v[224:227], v[108:111]
	s_waitcnt lgkmcnt(0)
	v_mfma_f32_16x16x32_bf16 v[76:79], v[156:159], v[240:243], v[76:79]
	v_mfma_f32_16x16x32_bf16 v[68:71], v[170:173], v[240:243], v[68:71]
	v_mfma_f32_16x16x32_bf16 v[144:147], v[174:177], v[190:193], v[144:147]
	v_mfma_f32_16x16x32_bf16 v[136:139], v[182:185], v[190:193], v[136:139]
	v_mfma_f32_16x16x32_bf16 v[128:131], v[174:177], v[198:201], v[128:131]
	v_mfma_f32_16x16x32_bf16 v[120:123], v[182:185], v[198:201], v[120:123]
	v_mfma_f32_16x16x32_bf16 v[112:115], v[174:177], v[220:223], v[112:115]
	v_mfma_f32_16x16x32_bf16 v[104:107], v[182:185], v[220:223], v[104:107]
	v_mfma_f32_16x16x32_bf16 v[72:75], v[174:177], v[228:231], v[72:75]
	v_mfma_f32_16x16x32_bf16 v[64:67], v[182:185], v[228:231], v[64:67]
	v_mfma_f32_16x16x32_bf16 v[144:147], v[178:181], v[194:197], v[144:147]
	v_mfma_f32_16x16x32_bf16 v[136:139], v[186:189], v[194:197], v[136:139]
	v_mfma_f32_16x16x32_bf16 v[128:131], v[178:181], v[202:205], v[128:131]
	v_mfma_f32_16x16x32_bf16 v[120:123], v[186:189], v[202:205], v[120:123]
	v_mfma_f32_16x16x32_bf16 v[112:115], v[178:181], v[224:227], v[112:115]
	v_mfma_f32_16x16x32_bf16 v[104:107], v[186:189], v[224:227], v[104:107]
	v_mfma_f32_16x16x32_bf16 v[72:75], v[178:181], v[240:243], v[72:75]
	v_mfma_f32_16x16x32_bf16 v[64:67], v[186:189], v[240:243], v[64:67]
	s_barrier
	ds_read_b128 v[190:193], v169 offset:49152
	ds_read_b128 v[194:197], v169 offset:50176
	ds_read_b128 v[198:201], v169 offset:51200
	ds_read_b128 v[202:205], v169 offset:52224
	ds_read_b128 v[220:223], v169 offset:53248
	ds_read_b128 v[224:227], v169 offset:54272
	ds_read_b128 v[228:231], v169 offset:55296
	ds_read_b128 v[240:243], v169 offset:56320
	s_or_b32 s56, s55, 0x4000
	s_mov_b32 m0, s16
	s_nop 0
	buffer_load_dwordx4 v166, s[28:31], s56 offen lds
	s_add_i32 s55, s55, 0x84000
	s_mov_b32 m0, s17
	s_nop 0
	buffer_load_dwordx4 v167, s[28:31], s56 offen lds
	s_nop 0
	s_mov_b32 m0, s34
	s_nop 0
	buffer_load_dwordx4 v166, s[28:31], s55 offen lds
	s_nop 0
	s_mov_b32 m0, s40
	s_nop 0
	buffer_load_dwordx4 v167, s[28:31], s55 offen lds
	s_nop 0
	s_mov_b32 m0, s18
	s_nop 0
	buffer_load_dwordx4 v166, s[24:27], s53 offen lds
	s_nop 0
	s_mov_b32 m0, s19
	s_nop 0
	buffer_load_dwordx4 v167, s[24:27], s53 offen lds
	s_waitcnt vmcnt(8)
	s_waitcnt lgkmcnt(0)
	s_barrier
	s_waitcnt lgkmcnt(7)
	v_mfma_f32_16x16x32_bf16 v[60:63], v[152:155], v[190:193], v[60:63]
	v_mfma_f32_16x16x32_bf16 v[52:55], v[160:163], v[190:193], v[52:55]
	s_waitcnt lgkmcnt(5)
	v_mfma_f32_16x16x32_bf16 v[44:47], v[152:155], v[198:201], v[44:47]
	v_mfma_f32_16x16x32_bf16 v[36:39], v[160:163], v[198:201], v[36:39]
	s_waitcnt lgkmcnt(3)
	v_mfma_f32_16x16x32_bf16 v[28:31], v[152:155], v[220:223], v[28:31]
	v_mfma_f32_16x16x32_bf16 v[20:23], v[160:163], v[220:223], v[20:23]
	s_waitcnt lgkmcnt(1)
	v_mfma_f32_16x16x32_bf16 v[12:15], v[152:155], v[228:231], v[12:15]
	v_mfma_f32_16x16x32_bf16 v[4:7], v[160:163], v[228:231], v[4:7]
	v_mfma_f32_16x16x32_bf16 v[60:63], v[156:159], v[194:197], v[60:63]
	v_mfma_f32_16x16x32_bf16 v[52:55], v[170:173], v[194:197], v[52:55]
	v_mfma_f32_16x16x32_bf16 v[44:47], v[156:159], v[202:205], v[44:47]
	v_mfma_f32_16x16x32_bf16 v[36:39], v[170:173], v[202:205], v[36:39]
	v_mfma_f32_16x16x32_bf16 v[28:31], v[156:159], v[224:227], v[28:31]
	v_mfma_f32_16x16x32_bf16 v[20:23], v[170:173], v[224:227], v[20:23]
	s_waitcnt lgkmcnt(0)
	v_mfma_f32_16x16x32_bf16 v[12:15], v[156:159], v[240:243], v[12:15]
	v_mfma_f32_16x16x32_bf16 v[4:7], v[170:173], v[240:243], v[4:7]
	v_mfma_f32_16x16x32_bf16 v[56:59], v[174:177], v[190:193], v[56:59]
	v_mfma_f32_16x16x32_bf16 v[48:51], v[182:185], v[190:193], v[48:51]
	v_mfma_f32_16x16x32_bf16 v[40:43], v[174:177], v[198:201], v[40:43]
	v_mfma_f32_16x16x32_bf16 v[32:35], v[182:185], v[198:201], v[32:35]
	v_mfma_f32_16x16x32_bf16 v[24:27], v[174:177], v[220:223], v[24:27]
	v_mfma_f32_16x16x32_bf16 v[16:19], v[182:185], v[220:223], v[16:19]
	v_mfma_f32_16x16x32_bf16 v[8:11], v[174:177], v[228:231], v[8:11]
	v_mfma_f32_16x16x32_bf16 v[0:3], v[182:185], v[228:231], v[0:3]
	v_mfma_f32_16x16x32_bf16 v[56:59], v[178:181], v[194:197], v[56:59]
	v_mfma_f32_16x16x32_bf16 v[48:51], v[186:189], v[194:197], v[48:51]
	v_mfma_f32_16x16x32_bf16 v[40:43], v[178:181], v[202:205], v[40:43]
	v_mfma_f32_16x16x32_bf16 v[32:35], v[186:189], v[202:205], v[32:35]
	v_mfma_f32_16x16x32_bf16 v[24:27], v[178:181], v[224:227], v[24:27]
	v_mfma_f32_16x16x32_bf16 v[16:19], v[186:189], v[224:227], v[16:19]
	v_mfma_f32_16x16x32_bf16 v[8:11], v[178:181], v[240:243], v[8:11]
	v_mfma_f32_16x16x32_bf16 v[0:3], v[186:189], v[240:243], v[0:3]
	s_barrier
	s_add_i32 s52, s52, 2
	s_add_i32 s37, s37, 0x8000
	s_add_i32 s51, s51, 0x8000

.Lab_p5:
	s_nop 0
	v_cvt_f32_u32_e32 v171, v171
	v_cvt_f32_u32_e32 v170, v170
	v_fmac_f32_e32 v170, 0x4f800000, v171
	v_fmamk_f32 v170, v170, 0x30000000, v234
	v_rsq_f32_e32 v178, v170
	s_nop 0
	v_mul_f32_e32 v174, 0xbfb8aa3b, v178
	v_pk_mul_f32 v[172:173], v[150:151], v[174:175] op_sel_hi:[1,0]
	v_pk_mul_f32 v[170:171], v[148:149], v[174:175] op_sel_hi:[1,0]
	v_pk_mul_f32 v[176:177], v[142:143], v[174:175] op_sel_hi:[1,0]
	v_pk_mul_f32 v[174:175], v[140:141], v[174:175] op_sel_hi:[1,0]
	v_mul_f32_e32 v178, v178, v178
	v_pk_mul_f32 v[180:181], v[146:147], v[178:179] op_sel_hi:[1,0]
	v_exp_f32_e32 v170, v170
	v_exp_f32_e32 v174, v174
	v_exp_f32_e32 v171, v171
	v_exp_f32_e32 v175, v175
	v_exp_f32_e32 v172, v172
	v_exp_f32_e32 v176, v176
	v_exp_f32_e32 v173, v173
	v_exp_f32_e32 v177, v177
	v_pk_mul_f32 v[182:183], v[144:145], v[178:179] op_sel_hi:[1,0]
	v_pk_add_f32 v[144:145], v[170:171], 1.0 op_sel_hi:[1,0]
	v_pk_add_f32 v[146:147], v[172:173], 1.0 op_sel_hi:[1,0]
	v_pk_add_f32 v[150:151], v[176:177], 1.0 op_sel_hi:[1,0]
	v_pk_add_f32 v[148:149], v[174:175], 1.0 op_sel_hi:[1,0]
	v_pk_mul_f32 v[138:139], v[138:139], v[178:179] op_sel_hi:[1,0]
	v_pk_mul_f32 v[136:137], v[136:137], v[178:179] op_sel_hi:[1,0]
	v_rcp_f32_e32 v144, v144
	v_rcp_f32_e32 v148, v148
	v_rcp_f32_e32 v145, v145
	v_rcp_f32_e32 v149, v149
	v_rcp_f32_e32 v146, v146
	v_rcp_f32_e32 v150, v150
	v_rcp_f32_e32 v147, v147
	v_rcp_f32_e32 v151, v151
	s_nop 0
	v_pk_mul_f32 v[140:141], v[180:181], v[146:147]
	v_pk_mul_f32 v[142:143], v[182:183], v[144:145]
	v_pk_mul_f32 v[144:145], v[138:139], v[150:151]
	v_pk_mul_f32 v[138:139], v[136:137], v[148:149]
	v_cvt_pk_bf16_f32 v136, v142, v143
	v_cvt_pk_bf16_f32 v137, v140, v141
	v_cvt_pk_bf16_f32 v138, v138, v139
	v_cvt_pk_bf16_f32 v139, v144, v145
	v_lshl_add_u64 v[140:141], s[36:37], 0, v[82:83]
	global_store_dwordx4 v[140:141], v[136:139], off nt
	s_nop 0
	s_nop 0
	v_cvt_f32_u32_e32 v136, v165
	v_cvt_f32_u32_e32 v137, v164
	v_fmac_f32_e32 v137, 0x4f800000, v136
	v_fmamk_f32 v136, v137, 0x30000000, v234
	v_rsq_f32_e32 v144, v136
	s_nop 0
	v_mul_f32_e32 v140, 0xbfb8aa3b, v144
	v_pk_mul_f32 v[138:139], v[134:135], v[140:141] op_sel_hi:[1,0]
	v_pk_mul_f32 v[136:137], v[132:133], v[140:141] op_sel_hi:[1,0]
	v_pk_mul_f32 v[142:143], v[126:127], v[140:141] op_sel_hi:[1,0]
	v_pk_mul_f32 v[140:141], v[124:125], v[140:141] op_sel_hi:[1,0]
	v_mul_f32_e32 v144, v144, v144
	v_pk_mul_f32 v[146:147], v[130:131], v[144:145] op_sel_hi:[1,0]
	v_exp_f32_e32 v136, v136
	v_exp_f32_e32 v140, v140
	v_exp_f32_e32 v137, v137
	v_exp_f32_e32 v141, v141
	v_exp_f32_e32 v138, v138
	v_exp_f32_e32 v142, v142
	v_exp_f32_e32 v139, v139
	v_exp_f32_e32 v143, v143
	v_pk_mul_f32 v[148:149], v[128:129], v[144:145] op_sel_hi:[1,0]
	v_pk_add_f32 v[128:129], v[136:137], 1.0 op_sel_hi:[1,0]
	v_pk_add_f32 v[130:131], v[138:139], 1.0 op_sel_hi:[1,0]
	v_pk_add_f32 v[134:135], v[142:143], 1.0 op_sel_hi:[1,0]
	v_pk_add_f32 v[132:133], v[140:141], 1.0 op_sel_hi:[1,0]
	v_pk_mul_f32 v[122:123], v[122:123], v[144:145] op_sel_hi:[1,0]
	v_pk_mul_f32 v[120:121], v[120:121], v[144:145] op_sel_hi:[1,0]
	v_rcp_f32_e32 v128, v128
	v_rcp_f32_e32 v132, v132
	v_rcp_f32_e32 v129, v129
	v_rcp_f32_e32 v133, v133
	v_rcp_f32_e32 v130, v130
	v_rcp_f32_e32 v134, v134
	v_rcp_f32_e32 v131, v131
	v_rcp_f32_e32 v135, v135
	s_nop 0
	v_pk_mul_f32 v[124:125], v[146:147], v[130:131]
	v_pk_mul_f32 v[126:127], v[148:149], v[128:129]
	v_pk_mul_f32 v[128:129], v[122:123], v[134:135]
	v_pk_mul_f32 v[122:123], v[120:121], v[132:133]
	v_cvt_pk_bf16_f32 v120, v126, v127
	v_cvt_pk_bf16_f32 v121, v124, v125
	v_cvt_pk_bf16_f32 v122, v122, v123
	v_cvt_pk_bf16_f32 v123, v128, v129
	v_lshl_add_u64 v[124:125], s[4:5], 0, v[82:83]
	global_store_dwordx4 v[124:125], v[120:123], off nt
	s_or_b32 s4, s33, 0x1000
	s_add_u32 s4, s20, s4
	s_nop 0
	v_cvt_f32_u32_e32 v120, v163
	v_cvt_f32_u32_e32 v121, v162
	s_addc_u32 s5, s68, 0
	v_fmac_f32_e32 v121, 0x4f800000, v120
	v_fmamk_f32 v120, v121, 0x30000000, v234
	v_rsq_f32_e32 v128, v120
	s_nop 0
	v_mul_f32_e32 v124, 0xbfb8aa3b, v128
	v_pk_mul_f32 v[122:123], v[118:119], v[124:125] op_sel_hi:[1,0]
	v_pk_mul_f32 v[120:121], v[116:117], v[124:125] op_sel_hi:[1,0]
	v_pk_mul_f32 v[126:127], v[110:111], v[124:125] op_sel_hi:[1,0]
	v_pk_mul_f32 v[124:125], v[108:109], v[124:125] op_sel_hi:[1,0]
	v_mul_f32_e32 v128, v128, v128
	v_pk_mul_f32 v[130:131], v[114:115], v[128:129] op_sel_hi:[1,0]
	v_exp_f32_e32 v120, v120
	v_exp_f32_e32 v124, v124
	v_exp_f32_e32 v121, v121
	v_exp_f32_e32 v125, v125
	v_exp_f32_e32 v122, v122
	v_exp_f32_e32 v126, v126
	v_exp_f32_e32 v123, v123
	v_exp_f32_e32 v127, v127
	v_pk_mul_f32 v[132:133], v[112:113], v[128:129] op_sel_hi:[1,0]
	v_pk_add_f32 v[112:113], v[120:121], 1.0 op_sel_hi:[1,0]
	v_pk_add_f32 v[114:115], v[122:123], 1.0 op_sel_hi:[1,0]
	v_pk_add_f32 v[118:119], v[126:127], 1.0 op_sel_hi:[1,0]
	v_pk_add_f32 v[116:117], v[124:125], 1.0 op_sel_hi:[1,0]
	v_pk_mul_f32 v[106:107], v[106:107], v[128:129] op_sel_hi:[1,0]
	v_pk_mul_f32 v[104:105], v[104:105], v[128:129] op_sel_hi:[1,0]
	v_rcp_f32_e32 v112, v112
	v_rcp_f32_e32 v116, v116
	v_rcp_f32_e32 v113, v113
	v_rcp_f32_e32 v117, v117
	v_rcp_f32_e32 v114, v114
	v_rcp_f32_e32 v118, v118
	v_rcp_f32_e32 v115, v115
	v_rcp_f32_e32 v119, v119
	s_nop 0
	v_pk_mul_f32 v[108:109], v[130:131], v[114:115]
	v_pk_mul_f32 v[110:111], v[132:133], v[112:113]
	v_pk_mul_f32 v[112:113], v[106:107], v[118:119]
	v_pk_mul_f32 v[106:107], v[104:105], v[116:117]
	v_cvt_pk_bf16_f32 v104, v110, v111
	v_cvt_pk_bf16_f32 v105, v108, v109
	v_cvt_pk_bf16_f32 v106, v106, v107
	v_cvt_pk_bf16_f32 v107, v112, v113
	v_lshl_add_u64 v[108:109], s[4:5], 0, v[82:83]
	global_store_dwordx4 v[108:109], v[104:107], off nt
	s_or_b32 s4, s33, 0x1800
	s_add_u32 s4, s20, s4
	s_nop 0
	v_cvt_f32_u32_e32 v104, v161
	v_cvt_f32_u32_e32 v105, v160
	s_addc_u32 s5, s68, 0
	v_fmac_f32_e32 v105, 0x4f800000, v104
	v_fmamk_f32 v104, v105, 0x30000000, v234
	v_rsq_f32_e32 v112, v104
	s_nop 0
	v_mul_f32_e32 v108, 0xbfb8aa3b, v112
	v_pk_mul_f32 v[106:107], v[78:79], v[108:109] op_sel_hi:[1,0]
	v_pk_mul_f32 v[104:105], v[76:77], v[108:109] op_sel_hi:[1,0]
	v_pk_mul_f32 v[110:111], v[70:71], v[108:109] op_sel_hi:[1,0]
	v_pk_mul_f32 v[108:109], v[68:69], v[108:109] op_sel_hi:[1,0]
	v_mul_f32_e32 v112, v112, v112
	v_pk_mul_f32 v[114:115], v[74:75], v[112:113] op_sel_hi:[1,0]
	v_exp_f32_e32 v104, v104
	v_exp_f32_e32 v108, v108
	v_exp_f32_e32 v105, v105
	v_exp_f32_e32 v109, v109
	v_exp_f32_e32 v106, v106
	v_exp_f32_e32 v110, v110
	v_exp_f32_e32 v107, v107
	v_exp_f32_e32 v111, v111
	v_pk_mul_f32 v[116:117], v[72:73], v[112:113] op_sel_hi:[1,0]
	v_pk_add_f32 v[72:73], v[104:105], 1.0 op_sel_hi:[1,0]
	v_pk_add_f32 v[74:75], v[106:107], 1.0 op_sel_hi:[1,0]
	v_pk_add_f32 v[78:79], v[110:111], 1.0 op_sel_hi:[1,0]
	v_pk_add_f32 v[76:77], v[108:109], 1.0 op_sel_hi:[1,0]
	v_pk_mul_f32 v[66:67], v[66:67], v[112:113] op_sel_hi:[1,0]
	v_pk_mul_f32 v[64:65], v[64:65], v[112:113] op_sel_hi:[1,0]
	v_rcp_f32_e32 v72, v72
	v_rcp_f32_e32 v76, v76
	v_rcp_f32_e32 v73, v73
	v_rcp_f32_e32 v77, v77
	v_rcp_f32_e32 v74, v74
	v_rcp_f32_e32 v78, v78
	v_rcp_f32_e32 v75, v75
	v_rcp_f32_e32 v79, v79
	s_nop 0
	v_pk_mul_f32 v[68:69], v[114:115], v[74:75]
	v_pk_mul_f32 v[70:71], v[116:117], v[72:73]
	v_pk_mul_f32 v[72:73], v[66:67], v[78:79]
	v_pk_mul_f32 v[66:67], v[64:65], v[76:77]
	v_cvt_pk_bf16_f32 v64, v70, v71
	v_cvt_pk_bf16_f32 v65, v68, v69
	v_cvt_pk_bf16_f32 v66, v66, v67
	v_cvt_pk_bf16_f32 v67, v72, v73
	v_lshl_add_u64 v[68:69], s[4:5], 0, v[82:83]
	global_store_dwordx4 v[68:69], v[64:67], off nt
	s_add_i32 s4, s33, 0x160000
	s_add_u32 s4, s20, s4
	s_nop 0
	v_cvt_f32_u32_e32 v64, v159
	v_cvt_f32_u32_e32 v65, v158
	s_addc_u32 s5, s68, 0
	v_fmac_f32_e32 v65, 0x4f800000, v64
	v_fmamk_f32 v64, v65, 0x30000000, v234
	v_rsq_f32_e32 v72, v64
	s_nop 0
	v_mul_f32_e32 v68, 0xbfb8aa3b, v72
	v_pk_mul_f32 v[66:67], v[62:63], v[68:69] op_sel_hi:[1,0]
	v_pk_mul_f32 v[64:65], v[60:61], v[68:69] op_sel_hi:[1,0]
	v_pk_mul_f32 v[70:71], v[54:55], v[68:69] op_sel_hi:[1,0]
	v_pk_mul_f32 v[68:69], v[52:53], v[68:69] op_sel_hi:[1,0]
	v_mul_f32_e32 v72, v72, v72
	v_pk_mul_f32 v[74:75], v[58:59], v[72:73] op_sel_hi:[1,0]
	v_exp_f32_e32 v64, v64
	v_exp_f32_e32 v68, v68
	v_exp_f32_e32 v65, v65
	v_exp_f32_e32 v69, v69
	v_exp_f32_e32 v66, v66
	v_exp_f32_e32 v70, v70
	v_exp_f32_e32 v67, v67
	v_exp_f32_e32 v71, v71
	v_pk_mul_f32 v[76:77], v[56:57], v[72:73] op_sel_hi:[1,0]
	v_pk_add_f32 v[56:57], v[64:65], 1.0 op_sel_hi:[1,0]
	v_pk_add_f32 v[58:59], v[66:67], 1.0 op_sel_hi:[1,0]
	v_pk_add_f32 v[62:63], v[70:71], 1.0 op_sel_hi:[1,0]
	v_pk_add_f32 v[60:61], v[68:69], 1.0 op_sel_hi:[1,0]
	v_pk_mul_f32 v[50:51], v[50:51], v[72:73] op_sel_hi:[1,0]
	v_pk_mul_f32 v[48:49], v[48:49], v[72:73] op_sel_hi:[1,0]
	v_rcp_f32_e32 v56, v56
	v_rcp_f32_e32 v60, v60
	v_rcp_f32_e32 v57, v57
	v_rcp_f32_e32 v61, v61
	v_rcp_f32_e32 v58, v58
	v_rcp_f32_e32 v62, v62
	v_rcp_f32_e32 v59, v59
	v_rcp_f32_e32 v63, v63
	s_nop 0
	v_pk_mul_f32 v[52:53], v[74:75], v[58:59]
	v_pk_mul_f32 v[54:55], v[76:77], v[56:57]
	v_pk_mul_f32 v[56:57], v[50:51], v[62:63]
	v_pk_mul_f32 v[50:51], v[48:49], v[60:61]
	v_cvt_pk_bf16_f32 v48, v54, v55
	v_cvt_pk_bf16_f32 v49, v52, v53
	v_cvt_pk_bf16_f32 v50, v50, v51
	v_cvt_pk_bf16_f32 v51, v56, v57
	v_lshl_add_u64 v[52:53], s[4:5], 0, v[82:83]
	global_store_dwordx4 v[52:53], v[48:51], off nt
	s_add_i32 s4, s33, 0x160800
	s_add_u32 s4, s20, s4
	s_nop 0
	v_cvt_f32_u32_e32 v48, v157
	v_cvt_f32_u32_e32 v49, v156
	s_addc_u32 s5, s68, 0
	v_fmac_f32_e32 v49, 0x4f800000, v48
	v_fmamk_f32 v48, v49, 0x30000000, v234
	v_rsq_f32_e32 v56, v48
	s_nop 0
	v_mul_f32_e32 v52, 0xbfb8aa3b, v56
	v_pk_mul_f32 v[50:51], v[46:47], v[52:53] op_sel_hi:[1,0]
	v_pk_mul_f32 v[48:49], v[44:45], v[52:53] op_sel_hi:[1,0]
	v_pk_mul_f32 v[54:55], v[38:39], v[52:53] op_sel_hi:[1,0]
	v_pk_mul_f32 v[52:53], v[36:37], v[52:53] op_sel_hi:[1,0]
	v_mul_f32_e32 v56, v56, v56
	v_pk_mul_f32 v[58:59], v[42:43], v[56:57] op_sel_hi:[1,0]
	v_exp_f32_e32 v48, v48
	v_exp_f32_e32 v52, v52
	v_exp_f32_e32 v49, v49
	v_exp_f32_e32 v53, v53
	v_exp_f32_e32 v50, v50
	v_exp_f32_e32 v54, v54
	v_exp_f32_e32 v51, v51
	v_exp_f32_e32 v55, v55
	v_pk_mul_f32 v[60:61], v[40:41], v[56:57] op_sel_hi:[1,0]
	v_pk_add_f32 v[40:41], v[48:49], 1.0 op_sel_hi:[1,0]
	v_pk_add_f32 v[42:43], v[50:51], 1.0 op_sel_hi:[1,0]
	v_pk_add_f32 v[46:47], v[54:55], 1.0 op_sel_hi:[1,0]
	v_pk_add_f32 v[44:45], v[52:53], 1.0 op_sel_hi:[1,0]
	v_pk_mul_f32 v[34:35], v[34:35], v[56:57] op_sel_hi:[1,0]
	v_pk_mul_f32 v[32:33], v[32:33], v[56:57] op_sel_hi:[1,0]
	v_rcp_f32_e32 v40, v40
	v_rcp_f32_e32 v44, v44
	v_rcp_f32_e32 v41, v41
	v_rcp_f32_e32 v45, v45
	v_rcp_f32_e32 v42, v42
	v_rcp_f32_e32 v46, v46
	v_rcp_f32_e32 v43, v43
	v_rcp_f32_e32 v47, v47
	s_nop 0
	v_pk_mul_f32 v[36:37], v[58:59], v[42:43]
	v_pk_mul_f32 v[38:39], v[60:61], v[40:41]
	v_pk_mul_f32 v[40:41], v[34:35], v[46:47]
	v_pk_mul_f32 v[34:35], v[32:33], v[44:45]
	v_cvt_pk_bf16_f32 v32, v38, v39
	v_cvt_pk_bf16_f32 v33, v36, v37
	v_cvt_pk_bf16_f32 v34, v34, v35
	v_cvt_pk_bf16_f32 v35, v40, v41
	v_lshl_add_u64 v[36:37], s[4:5], 0, v[82:83]
	global_store_dwordx4 v[36:37], v[32:35], off nt
	s_add_i32 s4, s33, 0x161000
	s_add_u32 s4, s20, s4
	s_nop 0
	v_cvt_f32_u32_e32 v32, v155
	v_cvt_f32_u32_e32 v33, v154
	s_addc_u32 s5, s68, 0
	s_add_i32 s33, s33, 0x161800
	v_fmac_f32_e32 v33, 0x4f800000, v32
	v_fmamk_f32 v32, v33, 0x30000000, v234
	v_rsq_f32_e32 v40, v32
	s_nop 0
	v_mul_f32_e32 v36, 0xbfb8aa3b, v40
	v_pk_mul_f32 v[34:35], v[30:31], v[36:37] op_sel_hi:[1,0]
	v_pk_mul_f32 v[32:33], v[28:29], v[36:37] op_sel_hi:[1,0]
	v_pk_mul_f32 v[38:39], v[22:23], v[36:37] op_sel_hi:[1,0]
	v_pk_mul_f32 v[36:37], v[20:21], v[36:37] op_sel_hi:[1,0]
	v_mul_f32_e32 v40, v40, v40
	v_pk_mul_f32 v[42:43], v[26:27], v[40:41] op_sel_hi:[1,0]
	v_exp_f32_e32 v32, v32
	v_exp_f32_e32 v36, v36
	v_exp_f32_e32 v33, v33
	v_exp_f32_e32 v37, v37
	v_exp_f32_e32 v34, v34
	v_exp_f32_e32 v38, v38
	v_exp_f32_e32 v35, v35
	v_exp_f32_e32 v39, v39
	v_pk_mul_f32 v[44:45], v[24:25], v[40:41] op_sel_hi:[1,0]
	v_pk_add_f32 v[24:25], v[32:33], 1.0 op_sel_hi:[1,0]
	v_pk_add_f32 v[26:27], v[34:35], 1.0 op_sel_hi:[1,0]
	v_pk_add_f32 v[30:31], v[38:39], 1.0 op_sel_hi:[1,0]
	v_pk_add_f32 v[28:29], v[36:37], 1.0 op_sel_hi:[1,0]
	v_pk_mul_f32 v[18:19], v[18:19], v[40:41] op_sel_hi:[1,0]
	v_pk_mul_f32 v[16:17], v[16:17], v[40:41] op_sel_hi:[1,0]
	v_rcp_f32_e32 v24, v24
	v_rcp_f32_e32 v28, v28
	v_rcp_f32_e32 v25, v25
	v_rcp_f32_e32 v29, v29
	v_rcp_f32_e32 v26, v26
	v_rcp_f32_e32 v30, v30
	v_rcp_f32_e32 v27, v27
	v_rcp_f32_e32 v31, v31
	s_nop 0
	v_pk_mul_f32 v[20:21], v[42:43], v[26:27]
	v_pk_mul_f32 v[22:23], v[44:45], v[24:25]
	v_pk_mul_f32 v[24:25], v[18:19], v[30:31]
	v_pk_mul_f32 v[18:19], v[16:17], v[28:29]
	v_cvt_pk_bf16_f32 v16, v22, v23
	v_cvt_pk_bf16_f32 v17, v20, v21
	v_cvt_pk_bf16_f32 v18, v18, v19
	v_cvt_pk_bf16_f32 v19, v24, v25
	v_lshl_add_u64 v[20:21], s[4:5], 0, v[82:83]
	global_store_dwordx4 v[20:21], v[16:19], off nt
	s_add_u32 s4, s20, s33
	s_addc_u32 s5, s68, 0
	s_nop 0
	v_cvt_f32_u32_e32 v16, v153
	v_cvt_f32_u32_e32 v17, v152
	s_andn2_b64 vcc, exec, s[38:39]
	v_fmac_f32_e32 v17, 0x4f800000, v16
	v_fmamk_f32 v16, v17, 0x30000000, v234
	v_rsq_f32_e32 v24, v16
	s_nop 0
	v_mul_f32_e32 v20, 0xbfb8aa3b, v24
	v_pk_mul_f32 v[18:19], v[14:15], v[20:21] op_sel_hi:[1,0]
	v_pk_mul_f32 v[16:17], v[12:13], v[20:21] op_sel_hi:[1,0]
	v_pk_mul_f32 v[22:23], v[6:7], v[20:21] op_sel_hi:[1,0]
	v_pk_mul_f32 v[20:21], v[4:5], v[20:21] op_sel_hi:[1,0]
	v_mul_f32_e32 v24, v24, v24
	v_pk_mul_f32 v[26:27], v[10:11], v[24:25] op_sel_hi:[1,0]
	v_exp_f32_e32 v16, v16
	v_exp_f32_e32 v20, v20
	v_exp_f32_e32 v17, v17
	v_exp_f32_e32 v21, v21
	v_exp_f32_e32 v18, v18
	v_exp_f32_e32 v22, v22
	v_exp_f32_e32 v19, v19
	v_exp_f32_e32 v23, v23
	v_pk_mul_f32 v[28:29], v[8:9], v[24:25] op_sel_hi:[1,0]
	v_pk_add_f32 v[8:9], v[16:17], 1.0 op_sel_hi:[1,0]
	v_pk_add_f32 v[10:11], v[18:19], 1.0 op_sel_hi:[1,0]
	v_pk_add_f32 v[14:15], v[22:23], 1.0 op_sel_hi:[1,0]
	v_pk_add_f32 v[12:13], v[20:21], 1.0 op_sel_hi:[1,0]
	v_pk_mul_f32 v[2:3], v[2:3], v[24:25] op_sel_hi:[1,0]
	v_pk_mul_f32 v[0:1], v[0:1], v[24:25] op_sel_hi:[1,0]
	v_rcp_f32_e32 v8, v8
	v_rcp_f32_e32 v12, v12
	v_rcp_f32_e32 v9, v9
	v_rcp_f32_e32 v13, v13
	v_rcp_f32_e32 v10, v10
	v_rcp_f32_e32 v14, v14
	v_rcp_f32_e32 v11, v11
	v_rcp_f32_e32 v15, v15
	s_nop 0
	v_pk_mul_f32 v[4:5], v[26:27], v[10:11]
	v_pk_mul_f32 v[6:7], v[28:29], v[8:9]
	v_pk_mul_f32 v[8:9], v[2:3], v[14:15]
	v_pk_mul_f32 v[2:3], v[0:1], v[12:13]
	v_cvt_pk_bf16_f32 v0, v6, v7
	v_cvt_pk_bf16_f32 v1, v4, v5
	v_cvt_pk_bf16_f32 v2, v2, v3
	v_cvt_pk_bf16_f32 v3, v8, v9
	v_lshl_add_u64 v[4:5], s[4:5], 0, v[82:83]
	s_mov_b64 s[4:5], -1
	global_store_dwordx4 v[4:5], v[0:3], off nt
	s_cbranch_vccnz .LBB0_791
	s_andn2_b64 vcc, exec, s[0:1]
	s_cbranch_vccnz .LBB0_790
	s_barrier
	s_branch .LBB0_790

.Lpeel_p6:
	s_waitcnt lgkmcnt(0)
	s_add_i32 s11, s8, 0xffea4000
	s_cmpk_eq_i32 s10, 0x54
	s_cselect_b32 s13, s6, s11
	s_cselect_b32 s12, s7, s9
	s_or_b32 s11, s13, 0x4000
	s_mov_b32 m0, s87
	s_nop 0
	buffer_load_dwordx4 v220, s[20:23], s8 offen lds
	s_nop 0
	s_mov_b32 m0, s89
	s_nop 0
	buffer_load_dwordx4 v221, s[20:23], s8 offen lds
	s_waitcnt vmcnt(24)
	s_waitcnt lgkmcnt(0)
	s_barrier
	s_waitcnt lgkmcnt(7)
	v_mfma_f32_16x16x32_bf16 v[164:167], v[128:131], v[184:187], 0
	v_mfma_f32_16x16x32_bf16 v[160:163], v[152:155], v[184:187], 0
	s_waitcnt lgkmcnt(5)
	v_mfma_f32_16x16x32_bf16 v[136:139], v[128:131], v[192:195], 0
	v_mfma_f32_16x16x32_bf16 v[132:135], v[152:155], v[192:195], 0
	s_waitcnt lgkmcnt(3)
	v_mfma_f32_16x16x32_bf16 v[116:119], v[128:131], v[200:203], 0
	v_mfma_f32_16x16x32_bf16 v[112:115], v[152:155], v[200:203], 0
	s_waitcnt lgkmcnt(1)
	v_mfma_f32_16x16x32_bf16 v[76:79], v[128:131], v[224:227], 0
	v_mfma_f32_16x16x32_bf16 v[72:75], v[152:155], v[224:227], 0
	v_mfma_f32_16x16x32_bf16 v[164:167], v[140:143], v[188:191], v[164:167]
	v_mfma_f32_16x16x32_bf16 v[160:163], v[156:159], v[188:191], v[160:163]
	v_mfma_f32_16x16x32_bf16 v[136:139], v[140:143], v[196:199], v[136:139]
	v_mfma_f32_16x16x32_bf16 v[132:135], v[156:159], v[196:199], v[132:135]
	v_mfma_f32_16x16x32_bf16 v[116:119], v[140:143], v[204:207], v[116:119]
	v_mfma_f32_16x16x32_bf16 v[112:115], v[156:159], v[204:207], v[112:115]
	s_waitcnt lgkmcnt(0)
	v_mfma_f32_16x16x32_bf16 v[76:79], v[140:143], v[228:231], v[76:79]
	v_mfma_f32_16x16x32_bf16 v[72:75], v[156:159], v[228:231], v[72:75]
	v_mfma_f32_16x16x32_bf16 v[148:151], v[168:171], v[184:187], 0
	v_mfma_f32_16x16x32_bf16 v[144:147], v[176:179], v[184:187], 0
	v_mfma_f32_16x16x32_bf16 v[124:127], v[168:171], v[192:195], 0
	v_mfma_f32_16x16x32_bf16 v[120:123], v[176:179], v[192:195], 0
	v_mfma_f32_16x16x32_bf16 v[108:111], v[168:171], v[200:203], 0
	v_mfma_f32_16x16x32_bf16 v[104:107], v[176:179], v[200:203], 0
	v_mfma_f32_16x16x32_bf16 v[68:71], v[168:171], v[224:227], 0
	v_mfma_f32_16x16x32_bf16 v[64:67], v[176:179], v[224:227], 0
	v_mfma_f32_16x16x32_bf16 v[148:151], v[172:175], v[188:191], v[148:151]
	v_mfma_f32_16x16x32_bf16 v[144:147], v[180:183], v[188:191], v[144:147]
	v_mfma_f32_16x16x32_bf16 v[124:127], v[172:175], v[196:199], v[124:127]
	v_mfma_f32_16x16x32_bf16 v[120:123], v[180:183], v[196:199], v[120:123]
	v_mfma_f32_16x16x32_bf16 v[108:111], v[172:175], v[204:207], v[108:111]
	v_mfma_f32_16x16x32_bf16 v[104:107], v[180:183], v[204:207], v[104:107]
	v_mfma_f32_16x16x32_bf16 v[68:71], v[172:175], v[228:231], v[68:71]
	v_mfma_f32_16x16x32_bf16 v[64:67], v[180:183], v[228:231], v[64:67]
	s_barrier
	ds_read_b128 v[184:187], v223 offset:16384
	ds_read_b128 v[188:191], v223 offset:17408
	ds_read_b128 v[192:195], v223 offset:18432
	ds_read_b128 v[196:199], v223 offset:19456
	ds_read_b128 v[200:203], v223 offset:20480
	ds_read_b128 v[204:207], v223 offset:21504
	ds_read_b128 v[224:227], v223 offset:22528
	ds_read_b128 v[228:231], v223 offset:23552
	s_mov_b32 m0, s51
	s_nop 0
	buffer_load_dwordx4 v220, s[52:55], s12 offen lds
	s_add_i32 s14, s12, 0x160000
	s_mov_b32 m0, s74
	s_nop 0
	buffer_load_dwordx4 v221, s[52:55], s12 offen lds
	s_nop 0
	s_mov_b32 m0, s75
	s_nop 0
	buffer_load_dwordx4 v220, s[52:55], s14 offen lds
	s_nop 0
	s_mov_b32 m0, s76
	s_nop 0
	buffer_load_dwordx4 v221, s[52:55], s14 offen lds
	s_nop 0
	s_mov_b32 m0, s31
	s_nop 0
	buffer_load_dwordx4 v220, s[20:23], s13 offen lds
	s_nop 0
	s_mov_b32 m0, s77
	s_nop 0
	buffer_load_dwordx4 v221, s[20:23], s13 offen lds
	s_waitcnt vmcnt(24)
	s_waitcnt lgkmcnt(0)
	s_barrier
	s_waitcnt lgkmcnt(7)
	v_mfma_f32_16x16x32_bf16 v[60:63], v[128:131], v[184:187], 0
	v_mfma_f32_16x16x32_bf16 v[56:59], v[152:155], v[184:187], 0
	s_waitcnt lgkmcnt(5)
	v_mfma_f32_16x16x32_bf16 v[44:47], v[128:131], v[192:195], 0
	v_mfma_f32_16x16x32_bf16 v[40:43], v[152:155], v[192:195], 0
	s_waitcnt lgkmcnt(3)
	v_mfma_f32_16x16x32_bf16 v[28:31], v[128:131], v[200:203], 0
	v_mfma_f32_16x16x32_bf16 v[24:27], v[152:155], v[200:203], 0
	s_waitcnt lgkmcnt(1)
	v_mfma_f32_16x16x32_bf16 v[12:15], v[128:131], v[224:227], 0
	v_mfma_f32_16x16x32_bf16 v[8:11], v[152:155], v[224:227], 0
	v_mfma_f32_16x16x32_bf16 v[60:63], v[140:143], v[188:191], v[60:63]
	v_mfma_f32_16x16x32_bf16 v[56:59], v[156:159], v[188:191], v[56:59]
	v_mfma_f32_16x16x32_bf16 v[44:47], v[140:143], v[196:199], v[44:47]
	v_mfma_f32_16x16x32_bf16 v[40:43], v[156:159], v[196:199], v[40:43]
	v_mfma_f32_16x16x32_bf16 v[28:31], v[140:143], v[204:207], v[28:31]
	v_mfma_f32_16x16x32_bf16 v[24:27], v[156:159], v[204:207], v[24:27]
	s_waitcnt lgkmcnt(0)
	v_mfma_f32_16x16x32_bf16 v[12:15], v[140:143], v[228:231], v[12:15]
	v_mfma_f32_16x16x32_bf16 v[8:11], v[156:159], v[228:231], v[8:11]
	v_mfma_f32_16x16x32_bf16 v[52:55], v[168:171], v[184:187], 0
	v_mfma_f32_16x16x32_bf16 v[48:51], v[176:179], v[184:187], 0
	v_mfma_f32_16x16x32_bf16 v[36:39], v[168:171], v[192:195], 0
	v_mfma_f32_16x16x32_bf16 v[32:35], v[176:179], v[192:195], 0
	v_mfma_f32_16x16x32_bf16 v[20:23], v[168:171], v[200:203], 0
	v_mfma_f32_16x16x32_bf16 v[16:19], v[176:179], v[200:203], 0
	v_mfma_f32_16x16x32_bf16 v[4:7], v[168:171], v[224:227], 0
	v_mfma_f32_16x16x32_bf16 v[0:3], v[176:179], v[224:227], 0
	v_mfma_f32_16x16x32_bf16 v[52:55], v[172:175], v[188:191], v[52:55]
	v_mfma_f32_16x16x32_bf16 v[48:51], v[180:183], v[188:191], v[48:51]
	v_mfma_f32_16x16x32_bf16 v[36:39], v[172:175], v[196:199], v[36:39]
	v_mfma_f32_16x16x32_bf16 v[32:35], v[180:183], v[196:199], v[32:35]
	v_mfma_f32_16x16x32_bf16 v[20:23], v[172:175], v[204:207], v[20:23]
	v_mfma_f32_16x16x32_bf16 v[16:19], v[180:183], v[204:207], v[16:19]
	v_mfma_f32_16x16x32_bf16 v[4:7], v[172:175], v[228:231], v[4:7]
	v_mfma_f32_16x16x32_bf16 v[0:3], v[180:183], v[228:231], v[0:3]
	s_barrier
	v_add_u32_e32 v156, 0x18000, v222
	v_add_u32_e32 v180, 0x1c000, v222
	ds_read_b128 v[128:131], v156
	ds_read_b128 v[140:143], v156 offset:1024
	ds_read_b128 v[152:155], v156 offset:2048
	ds_read_b128 v[156:159], v156 offset:3072
	ds_read_b128 v[168:171], v180
	ds_read_b128 v[172:175], v180 offset:1024
	ds_read_b128 v[176:179], v180 offset:2048
	ds_read_b128 v[180:183], v180 offset:3072
	ds_read_b128 v[184:187], v223 offset:32768
	ds_read_b128 v[188:191], v223 offset:33792
	ds_read_b128 v[192:195], v223 offset:34816
	ds_read_b128 v[196:199], v223 offset:35840
	ds_read_b128 v[200:203], v223 offset:36864
	ds_read_b128 v[204:207], v223 offset:37888
	ds_read_b128 v[224:227], v223 offset:38912
	ds_read_b128 v[228:231], v223 offset:39936
	s_add_i32 s13, s13, 0x160000
	s_mov_b32 m0, s78
	s_nop 0
	buffer_load_dwordx4 v220, s[20:23], s13 offen lds
	s_nop 0
	s_mov_b32 m0, s79
	s_nop 0
	buffer_load_dwordx4 v221, s[20:23], s13 offen lds
	s_waitcnt vmcnt(8)
	s_waitcnt lgkmcnt(0)
	s_barrier
	s_waitcnt lgkmcnt(7)
	v_mfma_f32_16x16x32_bf16 v[164:167], v[128:131], v[184:187], v[164:167]
	v_mfma_f32_16x16x32_bf16 v[160:163], v[152:155], v[184:187], v[160:163]
	s_waitcnt lgkmcnt(5)
	v_mfma_f32_16x16x32_bf16 v[136:139], v[128:131], v[192:195], v[136:139]
	v_mfma_f32_16x16x32_bf16 v[132:135], v[152:155], v[192:195], v[132:135]
	s_waitcnt lgkmcnt(3)
	v_mfma_f32_16x16x32_bf16 v[116:119], v[128:131], v[200:203], v[116:119]
	v_mfma_f32_16x16x32_bf16 v[112:115], v[152:155], v[200:203], v[112:115]
	s_waitcnt lgkmcnt(1)
	v_mfma_f32_16x16x32_bf16 v[76:79], v[128:131], v[224:227], v[76:79]
	v_mfma_f32_16x16x32_bf16 v[72:75], v[152:155], v[224:227], v[72:75]
	v_mfma_f32_16x16x32_bf16 v[164:167], v[140:143], v[188:191], v[164:167]
	v_mfma_f32_16x16x32_bf16 v[160:163], v[156:159], v[188:191], v[160:163]
	v_mfma_f32_16x16x32_bf16 v[136:139], v[140:143], v[196:199], v[136:139]
	v_mfma_f32_16x16x32_bf16 v[132:135], v[156:159], v[196:199], v[132:135]
	v_mfma_f32_16x16x32_bf16 v[116:119], v[140:143], v[204:207], v[116:119]
	v_mfma_f32_16x16x32_bf16 v[112:115], v[156:159], v[204:207], v[112:115]
	s_waitcnt lgkmcnt(0)
	v_mfma_f32_16x16x32_bf16 v[76:79], v[140:143], v[228:231], v[76:79]
	v_mfma_f32_16x16x32_bf16 v[72:75], v[156:159], v[228:231], v[72:75]
	v_mfma_f32_16x16x32_bf16 v[148:151], v[168:171], v[184:187], v[148:151]
	v_mfma_f32_16x16x32_bf16 v[144:147], v[176:179], v[184:187], v[144:147]
	v_mfma_f32_16x16x32_bf16 v[124:127], v[168:171], v[192:195], v[124:127]
	v_mfma_f32_16x16x32_bf16 v[120:123], v[176:179], v[192:195], v[120:123]
	v_mfma_f32_16x16x32_bf16 v[108:111], v[168:171], v[200:203], v[108:111]
	v_mfma_f32_16x16x32_bf16 v[104:107], v[176:179], v[200:203], v[104:107]
	v_mfma_f32_16x16x32_bf16 v[68:71], v[168:171], v[224:227], v[68:71]
	v_mfma_f32_16x16x32_bf16 v[64:67], v[176:179], v[224:227], v[64:67]
	v_mfma_f32_16x16x32_bf16 v[148:151], v[172:175], v[188:191], v[148:151]
	v_mfma_f32_16x16x32_bf16 v[144:147], v[180:183], v[188:191], v[144:147]
	v_mfma_f32_16x16x32_bf16 v[124:127], v[172:175], v[196:199], v[124:127]
	v_mfma_f32_16x16x32_bf16 v[120:123], v[180:183], v[196:199], v[120:123]
	v_mfma_f32_16x16x32_bf16 v[108:111], v[172:175], v[204:207], v[108:111]
	v_mfma_f32_16x16x32_bf16 v[104:107], v[180:183], v[204:207], v[104:107]
	v_mfma_f32_16x16x32_bf16 v[68:71], v[172:175], v[228:231], v[68:71]
	v_mfma_f32_16x16x32_bf16 v[64:67], v[180:183], v[228:231], v[64:67]
	s_barrier
	ds_read_b128 v[184:187], v223 offset:49152
	ds_read_b128 v[188:191], v223 offset:50176
	ds_read_b128 v[192:195], v223 offset:51200
	ds_read_b128 v[196:199], v223 offset:52224
	ds_read_b128 v[200:203], v223 offset:53248
	ds_read_b128 v[204:207], v223 offset:54272
	ds_read_b128 v[224:227], v223 offset:55296
	ds_read_b128 v[228:231], v223 offset:56320
	s_or_b32 s13, s12, 0x4000
	s_mov_b32 m0, s34
	s_nop 0
	buffer_load_dwordx4 v220, s[52:55], s13 offen lds
	s_add_i32 s12, s12, 0x164000
	s_mov_b32 m0, s82
	s_nop 0
	buffer_load_dwordx4 v221, s[52:55], s13 offen lds
	s_nop 0
	s_mov_b32 m0, s85
	s_nop 0
	buffer_load_dwordx4 v220, s[52:55], s12 offen lds
	s_nop 0
	s_mov_b32 m0, s86
	s_nop 0
	buffer_load_dwordx4 v221, s[52:55], s12 offen lds
	s_nop 0
	s_mov_b32 m0, s83
	s_nop 0
	buffer_load_dwordx4 v220, s[20:23], s11 offen lds
	s_nop 0
	s_mov_b32 m0, s84
	s_nop 0
	buffer_load_dwordx4 v221, s[20:23], s11 offen lds
	s_waitcnt vmcnt(8)
	s_waitcnt lgkmcnt(0)
	s_barrier
	s_waitcnt lgkmcnt(7)
	v_mfma_f32_16x16x32_bf16 v[60:63], v[128:131], v[184:187], v[60:63]
	v_mfma_f32_16x16x32_bf16 v[56:59], v[152:155], v[184:187], v[56:59]
	s_waitcnt lgkmcnt(5)
	v_mfma_f32_16x16x32_bf16 v[44:47], v[128:131], v[192:195], v[44:47]
	v_mfma_f32_16x16x32_bf16 v[40:43], v[152:155], v[192:195], v[40:43]
	s_waitcnt lgkmcnt(3)
	v_mfma_f32_16x16x32_bf16 v[28:31], v[128:131], v[200:203], v[28:31]
	v_mfma_f32_16x16x32_bf16 v[24:27], v[152:155], v[200:203], v[24:27]
	s_waitcnt lgkmcnt(1)
	v_mfma_f32_16x16x32_bf16 v[12:15], v[128:131], v[224:227], v[12:15]
	v_mfma_f32_16x16x32_bf16 v[8:11], v[152:155], v[224:227], v[8:11]
	v_mfma_f32_16x16x32_bf16 v[60:63], v[140:143], v[188:191], v[60:63]
	v_mfma_f32_16x16x32_bf16 v[56:59], v[156:159], v[188:191], v[56:59]
	v_mfma_f32_16x16x32_bf16 v[44:47], v[140:143], v[196:199], v[44:47]
	v_mfma_f32_16x16x32_bf16 v[40:43], v[156:159], v[196:199], v[40:43]
	v_mfma_f32_16x16x32_bf16 v[28:31], v[140:143], v[204:207], v[28:31]
	v_mfma_f32_16x16x32_bf16 v[24:27], v[156:159], v[204:207], v[24:27]
	s_waitcnt lgkmcnt(0)
	v_mfma_f32_16x16x32_bf16 v[12:15], v[140:143], v[228:231], v[12:15]
	v_mfma_f32_16x16x32_bf16 v[8:11], v[156:159], v[228:231], v[8:11]
	v_mfma_f32_16x16x32_bf16 v[52:55], v[168:171], v[184:187], v[52:55]
	v_mfma_f32_16x16x32_bf16 v[48:51], v[176:179], v[184:187], v[48:51]
	v_mfma_f32_16x16x32_bf16 v[36:39], v[168:171], v[192:195], v[36:39]
	v_mfma_f32_16x16x32_bf16 v[32:35], v[176:179], v[192:195], v[32:35]
	v_mfma_f32_16x16x32_bf16 v[20:23], v[168:171], v[200:203], v[20:23]
	v_mfma_f32_16x16x32_bf16 v[16:19], v[176:179], v[200:203], v[16:19]
	v_mfma_f32_16x16x32_bf16 v[4:7], v[168:171], v[224:227], v[4:7]
	v_mfma_f32_16x16x32_bf16 v[0:3], v[176:179], v[224:227], v[0:3]
	v_mfma_f32_16x16x32_bf16 v[52:55], v[172:175], v[188:191], v[52:55]
	v_mfma_f32_16x16x32_bf16 v[48:51], v[180:183], v[188:191], v[48:51]
	v_mfma_f32_16x16x32_bf16 v[36:39], v[172:175], v[196:199], v[36:39]
	v_mfma_f32_16x16x32_bf16 v[32:35], v[180:183], v[196:199], v[32:35]
	v_mfma_f32_16x16x32_bf16 v[20:23], v[172:175], v[204:207], v[20:23]
	v_mfma_f32_16x16x32_bf16 v[16:19], v[180:183], v[204:207], v[16:19]
	v_mfma_f32_16x16x32_bf16 v[4:7], v[172:175], v[228:231], v[4:7]
	v_mfma_f32_16x16x32_bf16 v[0:3], v[180:183], v[228:231], v[0:3]
	s_barrier
	s_add_i32 s10, s10, 2
	s_add_i32 s8, s8, 0x8000
	s_add_i32 s9, s9, 0x8000
